# v16 + the 8 serial row-statistics loads of the gate/up and input-projection epilogues issued together at the top of the epilogue (counted waits); SwiGLU temporaries moved to v228-v249
# speedup vs baseline: 1.0155x; 1.0084x over previous
; __device__ __forceinline__ unsigned cvt_pk_bf16(float lo, float hi) { unsigned r; asm volatile("v_cvt_pk_bf16_f32 %0, %1, %2" : "=v"(r) : "v"(lo), "v"(hi)); return r; }
; __device__ __forceinline__ float silu_f(float g) { return g * __builtin_amdgcn_rcpf(1.0f + __expf(-g)); }
; __device__ __forceinline__ float row_rstd(const float* rss, int row) { if (!rss) return 1.0f; const f32x4 s = *(const f32x4*)(rss + 4 * (size_t)row); return __builtin_amdgcn_rsqf(((s[0] + s[1]) + (s[2] + s[3])) * (1.0f / 1024.0f) + 1e-6f); }
;     __device__ __forceinline__ void operator()(const f32x4 (&acc)[2][2][4][2], const Unit& u, int wr, int wc, int fr, int fq) const {
;     ...
;             for (int m = 0; m < 4; ++m) { const int row = row0 + ai * HALF + m * 16; bf16_t* rowp = O + (size_t)row * ldc + col0; const float rs = row_rstd(rss, row);
;                 const f32x4 g0 = acc[ai][0][m][0] * rs, g1 = acc[ai][0][m][1] * rs, u0 = acc[ai][1][m][0] * rs, u1 = acc[ai][1][m][1] * rs;
;                 u32x4 w;
;                 w.x = cvt_pk_bf16(silu_f(g0[0]) * u0[0], silu_f(g0[1]) * u0[1]); w.y = cvt_pk_bf16(silu_f(g0[2]) * u0[2], silu_f(g0[3]) * u0[3]);
;                 w.z = cvt_pk_bf16(silu_f(g1[0]) * u1[0], silu_f(g1[1]) * u1[1]); w.w = cvt_pk_bf16(silu_f(g1[2]) * u1[2], silu_f(g1[3]) * u1[3]);
;                 *(u32x4*)rowp = w; }
.LBB0_211:
	v_lshl_or_b32 v148, s0, 7, v159
	v_lshl_add_u32 v150, s1, 8, v1
	v_add_u32_e32 v194, 0, v150
	v_ashrrev_i32_e32 v195, 31, v194
	v_lshl_add_u64 v[194:195], v[194:195], 4, s[22:23]
	global_load_dwordx4 v[194:197], v[194:195], off
	v_add_u32_e32 v198, 16, v150
	v_ashrrev_i32_e32 v199, 31, v198
	v_lshl_add_u64 v[198:199], v[198:199], 4, s[22:23]
	global_load_dwordx4 v[198:201], v[198:199], off
	v_add_u32_e32 v202, 32, v150
	v_ashrrev_i32_e32 v203, 31, v202
	v_lshl_add_u64 v[202:203], v[202:203], 4, s[22:23]
	global_load_dwordx4 v[202:205], v[202:203], off
	v_add_u32_e32 v206, 48, v150
	v_ashrrev_i32_e32 v207, 31, v206
	v_lshl_add_u64 v[206:207], v[206:207], 4, s[22:23]
	global_load_dwordx4 v[206:209], v[206:207], off
	v_add_u32_e32 v210, 128, v150
	v_ashrrev_i32_e32 v211, 31, v210
	v_lshl_add_u64 v[210:211], v[210:211], 4, s[22:23]
	global_load_dwordx4 v[210:213], v[210:211], off
	v_add_u32_e32 v214, 144, v150
	v_ashrrev_i32_e32 v215, 31, v214
	v_lshl_add_u64 v[214:215], v[214:215], 4, s[22:23]
	global_load_dwordx4 v[214:217], v[214:215], off
	v_add_u32_e32 v218, 160, v150
	v_ashrrev_i32_e32 v219, 31, v218
	v_lshl_add_u64 v[218:219], v[218:219], 4, s[22:23]
	global_load_dwordx4 v[218:221], v[218:219], off
	v_add_u32_e32 v222, 176, v150
	v_ashrrev_i32_e32 v223, 31, v222
	v_lshl_add_u64 v[222:223], v[222:223], 4, s[22:23]
	global_load_dwordx4 v[222:225], v[222:223], off
	v_ashrrev_i32_e32 v149, 31, v148
	v_mov_b64_e32 v[146:147], s[20:21]
	v_ashrrev_i32_e32 v151, 31, v150
	v_mad_i64_i32 v[162:163], s[0:1], v150, s4, v[146:147]
	v_lshlrev_b64 v[148:149], 1, v[148:149]
	v_lshl_add_u64 v[166:167], v[162:163], 0, v[148:149]
	v_lshl_add_u64 v[162:163], v[150:151], 4, s[22:23]
	s_mov_b64 s[30:31], -1
	s_and_b64 vcc, exec, s[8:9]
	s_waitcnt vmcnt(7)
	v_mov_b64_e32 v[162:163], v[194:195]
	v_mov_b64_e32 v[164:165], v[196:197]
	v_mov_b32_e32 v168, v163
	v_mov_b32_e32 v169, v164
	v_mov_b32_e32 v163, v165
	v_pk_add_f32 v[162:163], v[168:169], v[162:163]
	s_nop 0
	v_add_f32_e32 v151, v162, v163
	v_fmamk_f32 v151, v151, 0x3a800000, v138
	v_rsq_f32_e32 v162, v151
	s_nop 0
	v_mul_f32_e32 v244, 0xbfb8aa3b, v162
	v_mul_f32_e32 v246, v162, v162
	v_mov_b32_e32 v248, 1.0
	v_pk_mul_f32 v[228:229], v[122:123], v[244:245] op_sel_hi:[1,0]
	v_pk_mul_f32 v[232:233], v[124:125], v[244:245] op_sel_hi:[1,0]
	v_pk_mul_f32 v[236:237], v[126:127], v[244:245] op_sel_hi:[1,0]
	v_pk_mul_f32 v[240:241], v[128:129], v[244:245] op_sel_hi:[1,0]
	v_exp_f32_e32 v228, v228
	v_exp_f32_e32 v229, v229
	v_exp_f32_e32 v232, v232
	v_exp_f32_e32 v233, v233
	v_exp_f32_e32 v236, v236
	v_exp_f32_e32 v237, v237
	v_exp_f32_e32 v240, v240
	v_exp_f32_e32 v241, v241
	v_pk_mul_f32 v[230:231], v[122:123], v[118:119]
	v_pk_mul_f32 v[234:235], v[124:125], v[120:121]
	v_pk_mul_f32 v[238:239], v[126:127], v[114:115]
	v_pk_mul_f32 v[242:243], v[128:129], v[116:117]
	v_pk_add_f32 v[228:229], v[228:229], v[248:249] op_sel_hi:[1,0]
	v_pk_add_f32 v[232:233], v[232:233], v[248:249] op_sel_hi:[1,0]
	v_pk_add_f32 v[236:237], v[236:237], v[248:249] op_sel_hi:[1,0]
	v_pk_add_f32 v[240:241], v[240:241], v[248:249] op_sel_hi:[1,0]
	v_rcp_f32_e32 v228, v228
	v_rcp_f32_e32 v229, v229
	v_rcp_f32_e32 v232, v232
	v_rcp_f32_e32 v233, v233
	v_rcp_f32_e32 v236, v236
	v_rcp_f32_e32 v237, v237
	v_rcp_f32_e32 v240, v240
	v_rcp_f32_e32 v241, v241
	v_pk_mul_f32 v[230:231], v[230:231], v[246:247] op_sel_hi:[1,0]
	v_pk_mul_f32 v[234:235], v[234:235], v[246:247] op_sel_hi:[1,0]
	v_pk_mul_f32 v[238:239], v[238:239], v[246:247] op_sel_hi:[1,0]
	v_pk_mul_f32 v[242:243], v[242:243], v[246:247] op_sel_hi:[1,0]
	v_pk_mul_f32 v[230:231], v[230:231], v[228:229]
	v_pk_mul_f32 v[234:235], v[234:235], v[232:233]
	v_pk_mul_f32 v[238:239], v[238:239], v[236:237]
	v_pk_mul_f32 v[242:243], v[242:243], v[240:241]
	v_cvt_pk_bf16_f32 v114, v230, v231
	v_cvt_pk_bf16_f32 v115, v234, v235
	v_cvt_pk_bf16_f32 v116, v238, v239
	v_cvt_pk_bf16_f32 v117, v242, v243
	global_store_dwordx4 v[166:167], v[114:117], off
	s_nop 1
	v_or_b32_e32 v116, 16, v150
	v_ashrrev_i32_e32 v117, 31, v116
	v_mad_i64_i32 v[114:115], s[0:1], v116, s4, v[146:147]
	v_lshl_add_u64 v[116:117], v[116:117], 4, s[22:23]
	v_lshl_add_u64 v[114:115], v[114:115], 0, v[148:149]
	s_waitcnt vmcnt(7)
	v_mov_b64_e32 v[116:117], v[198:199]
	v_mov_b64_e32 v[118:119], v[200:201]
	v_mov_b32_e32 v120, v117
	v_mov_b32_e32 v121, v118
	v_mov_b32_e32 v117, v119
	v_pk_add_f32 v[116:117], v[120:121], v[116:117]
	s_nop 0
	v_add_f32_e32 v116, v116, v117
	v_fmamk_f32 v116, v116, 0x3a800000, v138
	v_rsq_f32_e32 v116, v116
	s_nop 0
	v_mul_f32_e32 v244, 0xbfb8aa3b, v116
	v_mul_f32_e32 v246, v116, v116
	v_mov_b32_e32 v248, 1.0
	v_pk_mul_f32 v[228:229], v[110:111], v[244:245] op_sel_hi:[1,0]
	v_pk_mul_f32 v[232:233], v[112:113], v[244:245] op_sel_hi:[1,0]
	v_pk_mul_f32 v[236:237], v[106:107], v[244:245] op_sel_hi:[1,0]
	v_pk_mul_f32 v[240:241], v[108:109], v[244:245] op_sel_hi:[1,0]
	v_exp_f32_e32 v228, v228
	v_exp_f32_e32 v229, v229
	v_exp_f32_e32 v232, v232
	v_exp_f32_e32 v233, v233
	v_exp_f32_e32 v236, v236
	v_exp_f32_e32 v237, v237
	v_exp_f32_e32 v240, v240
	v_exp_f32_e32 v241, v241
	v_pk_mul_f32 v[230:231], v[110:111], v[102:103]
	v_pk_mul_f32 v[234:235], v[112:113], v[104:105]
	v_pk_mul_f32 v[238:239], v[106:107], v[98:99]
	v_pk_mul_f32 v[242:243], v[108:109], v[100:101]
	v_pk_add_f32 v[228:229], v[228:229], v[248:249] op_sel_hi:[1,0]
	v_pk_add_f32 v[232:233], v[232:233], v[248:249] op_sel_hi:[1,0]
	v_pk_add_f32 v[236:237], v[236:237], v[248:249] op_sel_hi:[1,0]
	v_pk_add_f32 v[240:241], v[240:241], v[248:249] op_sel_hi:[1,0]
	v_rcp_f32_e32 v228, v228
	v_rcp_f32_e32 v229, v229
	v_rcp_f32_e32 v232, v232
	v_rcp_f32_e32 v233, v233
	v_rcp_f32_e32 v236, v236
	v_rcp_f32_e32 v237, v237
	v_rcp_f32_e32 v240, v240
	v_rcp_f32_e32 v241, v241
	v_pk_mul_f32 v[230:231], v[230:231], v[246:247] op_sel_hi:[1,0]
	v_pk_mul_f32 v[234:235], v[234:235], v[246:247] op_sel_hi:[1,0]
	v_pk_mul_f32 v[238:239], v[238:239], v[246:247] op_sel_hi:[1,0]
	v_pk_mul_f32 v[242:243], v[242:243], v[246:247] op_sel_hi:[1,0]
	v_pk_mul_f32 v[230:231], v[230:231], v[228:229]
	v_pk_mul_f32 v[234:235], v[234:235], v[232:233]
	v_pk_mul_f32 v[238:239], v[238:239], v[236:237]
	v_pk_mul_f32 v[242:243], v[242:243], v[240:241]
	v_cvt_pk_bf16_f32 v98, v230, v231
	v_cvt_pk_bf16_f32 v99, v234, v235
	v_cvt_pk_bf16_f32 v100, v238, v239
	v_cvt_pk_bf16_f32 v101, v242, v243
	global_store_dwordx4 v[114:115], v[98:101], off
	s_nop 1
	v_or_b32_e32 v100, 32, v150
	v_ashrrev_i32_e32 v101, 31, v100
	v_mad_i64_i32 v[98:99], s[0:1], v100, s4, v[146:147]
	v_lshl_add_u64 v[100:101], v[100:101], 4, s[22:23]
	v_lshl_add_u64 v[98:99], v[98:99], 0, v[148:149]
	s_waitcnt vmcnt(7)
; __device__ __forceinline__ unsigned cvt_pk_bf16(float lo, float hi) { unsigned r; asm volatile("v_cvt_pk_bf16_f32 %0, %1, %2" : "=v"(r) : "v"(lo), "v"(hi)); return r; }
; __device__ __forceinline__ float silu_f(float g) { return g * __builtin_amdgcn_rcpf(1.0f + __expf(-g)); }
; __device__ __forceinline__ float row_rstd(const float* rss, int row) { if (!rss) return 1.0f; const f32x4 s = *(const f32x4*)(rss + 4 * (size_t)row); return __builtin_amdgcn_rsqf(((s[0] + s[1]) + (s[2] + s[3])) * (1.0f / 1024.0f) + 1e-6f); }
;     __device__ __forceinline__ void operator()(const f32x4 (&acc)[2][2][4][2], const Unit& u, int wr, int wc, int fr, int fq) const {
;     ...
;             for (int m = 0; m < 4; ++m) { const int row = row0 + ai * HALF + m * 16; bf16_t* rowp = O + (size_t)row * ldc + col0; const float rs = row_rstd(rss, row);
;                 const f32x4 g0 = acc[ai][0][m][0] * rs, g1 = acc[ai][0][m][1] * rs, u0 = acc[ai][1][m][0] * rs, u1 = acc[ai][1][m][1] * rs;
;                 u32x4 w;
;                 w.x = cvt_pk_bf16(silu_f(g0[0]) * u0[0], silu_f(g0[1]) * u0[1]); w.y = cvt_pk_bf16(silu_f(g0[2]) * u0[2], silu_f(g0[3]) * u0[3]);
;                 w.z = cvt_pk_bf16(silu_f(g1[0]) * u1[0], silu_f(g1[1]) * u1[1]); w.w = cvt_pk_bf16(silu_f(g1[2]) * u1[2], silu_f(g1[3]) * u1[3]);
;                 *(u32x4*)rowp = w; }
	v_mov_b64_e32 v[100:101], v[202:203]
	v_mov_b64_e32 v[102:103], v[204:205]
	v_mov_b32_e32 v104, v101
	v_mov_b32_e32 v105, v102
	v_mov_b32_e32 v101, v103
	v_pk_add_f32 v[100:101], v[104:105], v[100:101]
	s_nop 0
	v_add_f32_e32 v100, v100, v101
	v_fmamk_f32 v100, v100, 0x3a800000, v138
	v_rsq_f32_e32 v100, v100
	s_nop 0
	v_mul_f32_e32 v244, 0xbfb8aa3b, v100
	v_mul_f32_e32 v246, v100, v100
	v_mov_b32_e32 v248, 1.0
	v_pk_mul_f32 v[228:229], v[94:95], v[244:245] op_sel_hi:[1,0]
	v_pk_mul_f32 v[232:233], v[96:97], v[244:245] op_sel_hi:[1,0]
	v_pk_mul_f32 v[236:237], v[90:91], v[244:245] op_sel_hi:[1,0]
	v_pk_mul_f32 v[240:241], v[92:93], v[244:245] op_sel_hi:[1,0]
	v_exp_f32_e32 v228, v228
	v_exp_f32_e32 v229, v229
	v_exp_f32_e32 v232, v232
	v_exp_f32_e32 v233, v233
	v_exp_f32_e32 v236, v236
	v_exp_f32_e32 v237, v237
	v_exp_f32_e32 v240, v240
	v_exp_f32_e32 v241, v241
	v_pk_mul_f32 v[230:231], v[94:95], v[86:87]
	v_pk_mul_f32 v[234:235], v[96:97], v[88:89]
	v_pk_mul_f32 v[238:239], v[90:91], v[82:83]
	v_pk_mul_f32 v[242:243], v[92:93], v[84:85]
	v_pk_add_f32 v[228:229], v[228:229], v[248:249] op_sel_hi:[1,0]
	v_pk_add_f32 v[232:233], v[232:233], v[248:249] op_sel_hi:[1,0]
	v_pk_add_f32 v[236:237], v[236:237], v[248:249] op_sel_hi:[1,0]
	v_pk_add_f32 v[240:241], v[240:241], v[248:249] op_sel_hi:[1,0]
	v_rcp_f32_e32 v228, v228
	v_rcp_f32_e32 v229, v229
	v_rcp_f32_e32 v232, v232
	v_rcp_f32_e32 v233, v233
	v_rcp_f32_e32 v236, v236
	v_rcp_f32_e32 v237, v237
	v_rcp_f32_e32 v240, v240
	v_rcp_f32_e32 v241, v241
	v_pk_mul_f32 v[230:231], v[230:231], v[246:247] op_sel_hi:[1,0]
	v_pk_mul_f32 v[234:235], v[234:235], v[246:247] op_sel_hi:[1,0]
	v_pk_mul_f32 v[238:239], v[238:239], v[246:247] op_sel_hi:[1,0]
	v_pk_mul_f32 v[242:243], v[242:243], v[246:247] op_sel_hi:[1,0]
	v_pk_mul_f32 v[230:231], v[230:231], v[228:229]
	v_pk_mul_f32 v[234:235], v[234:235], v[232:233]
	v_pk_mul_f32 v[238:239], v[238:239], v[236:237]
	v_pk_mul_f32 v[242:243], v[242:243], v[240:241]
	v_cvt_pk_bf16_f32 v82, v230, v231
	v_cvt_pk_bf16_f32 v83, v234, v235
	v_cvt_pk_bf16_f32 v84, v238, v239
	v_cvt_pk_bf16_f32 v85, v242, v243
	global_store_dwordx4 v[98:99], v[82:85], off
	s_nop 1
	v_or_b32_e32 v84, 48, v150
	v_ashrrev_i32_e32 v85, 31, v84
	v_mad_i64_i32 v[82:83], s[0:1], v84, s4, v[146:147]
	v_lshl_add_u64 v[84:85], v[84:85], 4, s[22:23]
	v_lshl_add_u64 v[82:83], v[82:83], 0, v[148:149]
	s_waitcnt vmcnt(7)
	v_mov_b64_e32 v[84:85], v[206:207]
	v_mov_b64_e32 v[86:87], v[208:209]
	v_mov_b32_e32 v88, v85
	v_mov_b32_e32 v89, v86
	v_mov_b32_e32 v85, v87
	v_pk_add_f32 v[84:85], v[88:89], v[84:85]
	s_nop 0
	v_add_f32_e32 v84, v84, v85
	v_fmamk_f32 v84, v84, 0x3a800000, v138
	v_rsq_f32_e32 v84, v84
	s_nop 0
	v_mul_f32_e32 v244, 0xbfb8aa3b, v84
	v_mul_f32_e32 v246, v84, v84
	v_mov_b32_e32 v248, 1.0
	v_pk_mul_f32 v[228:229], v[78:79], v[244:245] op_sel_hi:[1,0]
	v_pk_mul_f32 v[232:233], v[80:81], v[244:245] op_sel_hi:[1,0]
	v_pk_mul_f32 v[236:237], v[74:75], v[244:245] op_sel_hi:[1,0]
	v_pk_mul_f32 v[240:241], v[76:77], v[244:245] op_sel_hi:[1,0]
	v_exp_f32_e32 v228, v228
	v_exp_f32_e32 v229, v229
	v_exp_f32_e32 v232, v232
	v_exp_f32_e32 v233, v233
	v_exp_f32_e32 v236, v236
	v_exp_f32_e32 v237, v237
	v_exp_f32_e32 v240, v240
	v_exp_f32_e32 v241, v241
	v_pk_mul_f32 v[230:231], v[78:79], v[70:71]
	v_pk_mul_f32 v[234:235], v[80:81], v[72:73]
	v_pk_mul_f32 v[238:239], v[74:75], v[66:67]
	v_pk_mul_f32 v[242:243], v[76:77], v[68:69]
	v_pk_add_f32 v[228:229], v[228:229], v[248:249] op_sel_hi:[1,0]
	v_pk_add_f32 v[232:233], v[232:233], v[248:249] op_sel_hi:[1,0]
	v_pk_add_f32 v[236:237], v[236:237], v[248:249] op_sel_hi:[1,0]
	v_pk_add_f32 v[240:241], v[240:241], v[248:249] op_sel_hi:[1,0]
	v_rcp_f32_e32 v228, v228
	v_rcp_f32_e32 v229, v229
	v_rcp_f32_e32 v232, v232
	v_rcp_f32_e32 v233, v233
	v_rcp_f32_e32 v236, v236
	v_rcp_f32_e32 v237, v237
	v_rcp_f32_e32 v240, v240
	v_rcp_f32_e32 v241, v241
	v_pk_mul_f32 v[230:231], v[230:231], v[246:247] op_sel_hi:[1,0]
	v_pk_mul_f32 v[234:235], v[234:235], v[246:247] op_sel_hi:[1,0]
	v_pk_mul_f32 v[238:239], v[238:239], v[246:247] op_sel_hi:[1,0]
	v_pk_mul_f32 v[242:243], v[242:243], v[246:247] op_sel_hi:[1,0]
	v_pk_mul_f32 v[230:231], v[230:231], v[228:229]
	v_pk_mul_f32 v[234:235], v[234:235], v[232:233]
	v_pk_mul_f32 v[238:239], v[238:239], v[236:237]
	v_pk_mul_f32 v[242:243], v[242:243], v[240:241]
	v_cvt_pk_bf16_f32 v66, v230, v231
	v_cvt_pk_bf16_f32 v67, v234, v235
	v_cvt_pk_bf16_f32 v68, v238, v239
	v_cvt_pk_bf16_f32 v69, v242, v243
	global_store_dwordx4 v[82:83], v[66:69], off
	s_nop 1
	v_add_u32_e32 v68, 0x80, v150
	v_ashrrev_i32_e32 v69, 31, v68
	v_mad_i64_i32 v[66:67], s[0:1], v68, s4, v[146:147]
	v_lshl_add_u64 v[68:69], v[68:69], 4, s[22:23]
	v_lshl_add_u64 v[66:67], v[66:67], 0, v[148:149]
	s_waitcnt vmcnt(7)
; __device__ __forceinline__ unsigned cvt_pk_bf16(float lo, float hi) { unsigned r; asm volatile("v_cvt_pk_bf16_f32 %0, %1, %2" : "=v"(r) : "v"(lo), "v"(hi)); return r; }
; __device__ __forceinline__ float silu_f(float g) { return g * __builtin_amdgcn_rcpf(1.0f + __expf(-g)); }
; __device__ __forceinline__ float row_rstd(const float* rss, int row) { if (!rss) return 1.0f; const f32x4 s = *(const f32x4*)(rss + 4 * (size_t)row); return __builtin_amdgcn_rsqf(((s[0] + s[1]) + (s[2] + s[3])) * (1.0f / 1024.0f) + 1e-6f); }
;     __device__ __forceinline__ void operator()(const f32x4 (&acc)[2][2][4][2], const Unit& u, int wr, int wc, int fr, int fq) const {
;     ...
;             for (int m = 0; m < 4; ++m) { const int row = row0 + ai * HALF + m * 16; bf16_t* rowp = O + (size_t)row * ldc + col0; const float rs = row_rstd(rss, row);
;                 const f32x4 g0 = acc[ai][0][m][0] * rs, g1 = acc[ai][0][m][1] * rs, u0 = acc[ai][1][m][0] * rs, u1 = acc[ai][1][m][1] * rs;
;                 u32x4 w;
;                 w.x = cvt_pk_bf16(silu_f(g0[0]) * u0[0], silu_f(g0[1]) * u0[1]); w.y = cvt_pk_bf16(silu_f(g0[2]) * u0[2], silu_f(g0[3]) * u0[3]);
;                 w.z = cvt_pk_bf16(silu_f(g1[0]) * u1[0], silu_f(g1[1]) * u1[1]); w.w = cvt_pk_bf16(silu_f(g1[2]) * u1[2], silu_f(g1[3]) * u1[3]);
;                 *(u32x4*)rowp = w; }
	v_mov_b64_e32 v[68:69], v[210:211]
	v_mov_b64_e32 v[70:71], v[212:213]
	v_mov_b32_e32 v72, v69
	v_mov_b32_e32 v73, v70
	v_mov_b32_e32 v69, v71
	v_pk_add_f32 v[68:69], v[72:73], v[68:69]
	s_nop 0
	v_add_f32_e32 v68, v68, v69
	v_fmamk_f32 v68, v68, 0x3a800000, v138
	v_rsq_f32_e32 v68, v68
	s_nop 0
	v_mul_f32_e32 v244, 0xbfb8aa3b, v68
	v_mul_f32_e32 v246, v68, v68
	v_mov_b32_e32 v248, 1.0
	v_pk_mul_f32 v[228:229], v[62:63], v[244:245] op_sel_hi:[1,0]
	v_pk_mul_f32 v[232:233], v[64:65], v[244:245] op_sel_hi:[1,0]
	v_pk_mul_f32 v[236:237], v[58:59], v[244:245] op_sel_hi:[1,0]
	v_pk_mul_f32 v[240:241], v[60:61], v[244:245] op_sel_hi:[1,0]
	v_exp_f32_e32 v228, v228
	v_exp_f32_e32 v229, v229
	v_exp_f32_e32 v232, v232
	v_exp_f32_e32 v233, v233
	v_exp_f32_e32 v236, v236
	v_exp_f32_e32 v237, v237
	v_exp_f32_e32 v240, v240
	v_exp_f32_e32 v241, v241
	v_pk_mul_f32 v[230:231], v[62:63], v[54:55]
	v_pk_mul_f32 v[234:235], v[64:65], v[56:57]
	v_pk_mul_f32 v[238:239], v[58:59], v[50:51]
	v_pk_mul_f32 v[242:243], v[60:61], v[52:53]
	v_pk_add_f32 v[228:229], v[228:229], v[248:249] op_sel_hi:[1,0]
	v_pk_add_f32 v[232:233], v[232:233], v[248:249] op_sel_hi:[1,0]
	v_pk_add_f32 v[236:237], v[236:237], v[248:249] op_sel_hi:[1,0]
	v_pk_add_f32 v[240:241], v[240:241], v[248:249] op_sel_hi:[1,0]
	v_rcp_f32_e32 v228, v228
	v_rcp_f32_e32 v229, v229
	v_rcp_f32_e32 v232, v232
	v_rcp_f32_e32 v233, v233
	v_rcp_f32_e32 v236, v236
	v_rcp_f32_e32 v237, v237
	v_rcp_f32_e32 v240, v240
	v_rcp_f32_e32 v241, v241
	v_pk_mul_f32 v[230:231], v[230:231], v[246:247] op_sel_hi:[1,0]
	v_pk_mul_f32 v[234:235], v[234:235], v[246:247] op_sel_hi:[1,0]
	v_pk_mul_f32 v[238:239], v[238:239], v[246:247] op_sel_hi:[1,0]
	v_pk_mul_f32 v[242:243], v[242:243], v[246:247] op_sel_hi:[1,0]
	v_pk_mul_f32 v[230:231], v[230:231], v[228:229]
	v_pk_mul_f32 v[234:235], v[234:235], v[232:233]
	v_pk_mul_f32 v[238:239], v[238:239], v[236:237]
	v_pk_mul_f32 v[242:243], v[242:243], v[240:241]
	v_cvt_pk_bf16_f32 v50, v230, v231
	v_cvt_pk_bf16_f32 v51, v234, v235
	v_cvt_pk_bf16_f32 v52, v238, v239
	v_cvt_pk_bf16_f32 v53, v242, v243
	global_store_dwordx4 v[66:67], v[50:53], off
	s_nop 1
	v_add_u32_e32 v52, 0x90, v150
	v_ashrrev_i32_e32 v53, 31, v52
	v_mad_i64_i32 v[50:51], s[0:1], v52, s4, v[146:147]
	v_lshl_add_u64 v[52:53], v[52:53], 4, s[22:23]
	v_lshl_add_u64 v[50:51], v[50:51], 0, v[148:149]
	s_waitcnt vmcnt(7)
	v_mov_b64_e32 v[52:53], v[214:215]
	v_mov_b64_e32 v[54:55], v[216:217]
	v_mov_b32_e32 v56, v53
	v_mov_b32_e32 v57, v54
	v_mov_b32_e32 v53, v55
	v_pk_add_f32 v[52:53], v[56:57], v[52:53]
	s_nop 0
	v_add_f32_e32 v52, v52, v53
	v_fmamk_f32 v52, v52, 0x3a800000, v138
	v_rsq_f32_e32 v52, v52
	s_nop 0
	v_mul_f32_e32 v244, 0xbfb8aa3b, v52
	v_mul_f32_e32 v246, v52, v52
	v_mov_b32_e32 v248, 1.0
	v_pk_mul_f32 v[228:229], v[46:47], v[244:245] op_sel_hi:[1,0]
	v_pk_mul_f32 v[232:233], v[48:49], v[244:245] op_sel_hi:[1,0]
	v_pk_mul_f32 v[236:237], v[42:43], v[244:245] op_sel_hi:[1,0]
	v_pk_mul_f32 v[240:241], v[44:45], v[244:245] op_sel_hi:[1,0]
	v_exp_f32_e32 v228, v228
	v_exp_f32_e32 v229, v229
	v_exp_f32_e32 v232, v232
	v_exp_f32_e32 v233, v233
	v_exp_f32_e32 v236, v236
	v_exp_f32_e32 v237, v237
	v_exp_f32_e32 v240, v240
	v_exp_f32_e32 v241, v241
	v_pk_mul_f32 v[230:231], v[46:47], v[38:39]
	v_pk_mul_f32 v[234:235], v[48:49], v[40:41]
	v_pk_mul_f32 v[238:239], v[42:43], v[34:35]
	v_pk_mul_f32 v[242:243], v[44:45], v[36:37]
	v_pk_add_f32 v[228:229], v[228:229], v[248:249] op_sel_hi:[1,0]
	v_pk_add_f32 v[232:233], v[232:233], v[248:249] op_sel_hi:[1,0]
	v_pk_add_f32 v[236:237], v[236:237], v[248:249] op_sel_hi:[1,0]
	v_pk_add_f32 v[240:241], v[240:241], v[248:249] op_sel_hi:[1,0]
	v_rcp_f32_e32 v228, v228
	v_rcp_f32_e32 v229, v229
	v_rcp_f32_e32 v232, v232
	v_rcp_f32_e32 v233, v233
	v_rcp_f32_e32 v236, v236
	v_rcp_f32_e32 v237, v237
	v_rcp_f32_e32 v240, v240
	v_rcp_f32_e32 v241, v241
	v_pk_mul_f32 v[230:231], v[230:231], v[246:247] op_sel_hi:[1,0]
	v_pk_mul_f32 v[234:235], v[234:235], v[246:247] op_sel_hi:[1,0]
	v_pk_mul_f32 v[238:239], v[238:239], v[246:247] op_sel_hi:[1,0]
	v_pk_mul_f32 v[242:243], v[242:243], v[246:247] op_sel_hi:[1,0]
	v_pk_mul_f32 v[230:231], v[230:231], v[228:229]
	v_pk_mul_f32 v[234:235], v[234:235], v[232:233]
	v_pk_mul_f32 v[238:239], v[238:239], v[236:237]
	v_pk_mul_f32 v[242:243], v[242:243], v[240:241]
	v_cvt_pk_bf16_f32 v34, v230, v231
	v_cvt_pk_bf16_f32 v35, v234, v235
	v_cvt_pk_bf16_f32 v36, v238, v239
	v_cvt_pk_bf16_f32 v37, v242, v243
	global_store_dwordx4 v[50:51], v[34:37], off
	s_nop 1
	v_add_u32_e32 v36, 0xa0, v150
	v_ashrrev_i32_e32 v37, 31, v36
	v_mad_i64_i32 v[34:35], s[0:1], v36, s4, v[146:147]
	v_lshl_add_u64 v[36:37], v[36:37], 4, s[22:23]
	v_lshl_add_u64 v[34:35], v[34:35], 0, v[148:149]
	s_waitcnt vmcnt(7)
; __device__ __forceinline__ unsigned cvt_pk_bf16(float lo, float hi) { unsigned r; asm volatile("v_cvt_pk_bf16_f32 %0, %1, %2" : "=v"(r) : "v"(lo), "v"(hi)); return r; }
; __device__ __forceinline__ float silu_f(float g) { return g * __builtin_amdgcn_rcpf(1.0f + __expf(-g)); }
; __device__ __forceinline__ float row_rstd(const float* rss, int row) { if (!rss) return 1.0f; const f32x4 s = *(const f32x4*)(rss + 4 * (size_t)row); return __builtin_amdgcn_rsqf(((s[0] + s[1]) + (s[2] + s[3])) * (1.0f / 1024.0f) + 1e-6f); }
;     __device__ __forceinline__ void operator()(const f32x4 (&acc)[2][2][4][2], const Unit& u, int wr, int wc, int fr, int fq) const {
;     ...
;             for (int m = 0; m < 4; ++m) { const int row = row0 + ai * HALF + m * 16; bf16_t* rowp = O + (size_t)row * ldc + col0; const float rs = row_rstd(rss, row);
;                 const f32x4 g0 = acc[ai][0][m][0] * rs, g1 = acc[ai][0][m][1] * rs, u0 = acc[ai][1][m][0] * rs, u1 = acc[ai][1][m][1] * rs;
;                 u32x4 w;
;                 w.x = cvt_pk_bf16(silu_f(g0[0]) * u0[0], silu_f(g0[1]) * u0[1]); w.y = cvt_pk_bf16(silu_f(g0[2]) * u0[2], silu_f(g0[3]) * u0[3]);
;                 w.z = cvt_pk_bf16(silu_f(g1[0]) * u1[0], silu_f(g1[1]) * u1[1]); w.w = cvt_pk_bf16(silu_f(g1[2]) * u1[2], silu_f(g1[3]) * u1[3]);
;                 *(u32x4*)rowp = w; }
	v_mov_b64_e32 v[36:37], v[218:219]
	v_mov_b64_e32 v[38:39], v[220:221]
	v_mov_b32_e32 v40, v37
	v_mov_b32_e32 v41, v38
	v_mov_b32_e32 v37, v39
	v_pk_add_f32 v[36:37], v[40:41], v[36:37]
	s_nop 0
	v_add_f32_e32 v36, v36, v37
	v_fmamk_f32 v36, v36, 0x3a800000, v138
	v_rsq_f32_e32 v36, v36
	s_nop 0
	v_mul_f32_e32 v244, 0xbfb8aa3b, v36
	v_mul_f32_e32 v246, v36, v36
	v_mov_b32_e32 v248, 1.0
	v_pk_mul_f32 v[228:229], v[30:31], v[244:245] op_sel_hi:[1,0]
	v_pk_mul_f32 v[232:233], v[32:33], v[244:245] op_sel_hi:[1,0]
	v_pk_mul_f32 v[236:237], v[26:27], v[244:245] op_sel_hi:[1,0]
	v_pk_mul_f32 v[240:241], v[28:29], v[244:245] op_sel_hi:[1,0]
	v_exp_f32_e32 v228, v228
	v_exp_f32_e32 v229, v229
	v_exp_f32_e32 v232, v232
	v_exp_f32_e32 v233, v233
	v_exp_f32_e32 v236, v236
	v_exp_f32_e32 v237, v237
	v_exp_f32_e32 v240, v240
	v_exp_f32_e32 v241, v241
	v_pk_mul_f32 v[230:231], v[30:31], v[22:23]
	v_pk_mul_f32 v[234:235], v[32:33], v[24:25]
	v_pk_mul_f32 v[238:239], v[26:27], v[18:19]
	v_pk_mul_f32 v[242:243], v[28:29], v[20:21]
	v_pk_add_f32 v[228:229], v[228:229], v[248:249] op_sel_hi:[1,0]
	v_pk_add_f32 v[232:233], v[232:233], v[248:249] op_sel_hi:[1,0]
	v_pk_add_f32 v[236:237], v[236:237], v[248:249] op_sel_hi:[1,0]
	v_pk_add_f32 v[240:241], v[240:241], v[248:249] op_sel_hi:[1,0]
	v_rcp_f32_e32 v228, v228
	v_rcp_f32_e32 v229, v229
	v_rcp_f32_e32 v232, v232
	v_rcp_f32_e32 v233, v233
	v_rcp_f32_e32 v236, v236
	v_rcp_f32_e32 v237, v237
	v_rcp_f32_e32 v240, v240
	v_rcp_f32_e32 v241, v241
	v_pk_mul_f32 v[230:231], v[230:231], v[246:247] op_sel_hi:[1,0]
	v_pk_mul_f32 v[234:235], v[234:235], v[246:247] op_sel_hi:[1,0]
	v_pk_mul_f32 v[238:239], v[238:239], v[246:247] op_sel_hi:[1,0]
	v_pk_mul_f32 v[242:243], v[242:243], v[246:247] op_sel_hi:[1,0]
	v_pk_mul_f32 v[230:231], v[230:231], v[228:229]
	v_pk_mul_f32 v[234:235], v[234:235], v[232:233]
	v_pk_mul_f32 v[238:239], v[238:239], v[236:237]
	v_pk_mul_f32 v[242:243], v[242:243], v[240:241]
	v_cvt_pk_bf16_f32 v18, v230, v231
	v_cvt_pk_bf16_f32 v19, v234, v235
	v_cvt_pk_bf16_f32 v20, v238, v239
	v_cvt_pk_bf16_f32 v21, v242, v243
	global_store_dwordx4 v[34:35], v[18:21], off
	s_nop 1
	v_add_u32_e32 v18, 0xb0, v150
	v_ashrrev_i32_e32 v19, 31, v18
	v_lshl_add_u64 v[20:21], v[18:19], 4, s[22:23]
	s_waitcnt vmcnt(7)
	v_mov_b64_e32 v[20:21], v[222:223]
	v_mov_b64_e32 v[22:23], v[224:225]
	v_mov_b32_e32 v24, v21
	v_mov_b32_e32 v25, v22
	v_mov_b32_e32 v21, v23
	v_pk_add_f32 v[20:21], v[24:25], v[20:21]
	s_nop 0
	v_add_f32_e32 v19, v20, v21
	v_fmamk_f32 v19, v19, 0x3a800000, v138
	v_rsq_f32_e32 v20, v19
	s_nop 0
	v_mad_i64_i32 v[18:19], s[0:1], v18, s4, v[146:147]
	v_lshl_add_u64 v[18:19], v[18:19], 0, v[148:149]
	v_mul_f32_e32 v244, 0xbfb8aa3b, v20
	v_mul_f32_e32 v246, v20, v20
	v_mov_b32_e32 v248, 1.0
	v_pk_mul_f32 v[228:229], v[14:15], v[244:245] op_sel_hi:[1,0]
	v_pk_mul_f32 v[232:233], v[16:17], v[244:245] op_sel_hi:[1,0]
	v_pk_mul_f32 v[236:237], v[10:11], v[244:245] op_sel_hi:[1,0]
	v_pk_mul_f32 v[240:241], v[12:13], v[244:245] op_sel_hi:[1,0]
	v_exp_f32_e32 v228, v228
	v_exp_f32_e32 v229, v229
	v_exp_f32_e32 v232, v232
	v_exp_f32_e32 v233, v233
	v_exp_f32_e32 v236, v236
	v_exp_f32_e32 v237, v237
	v_exp_f32_e32 v240, v240
	v_exp_f32_e32 v241, v241
	v_pk_mul_f32 v[230:231], v[14:15], v[6:7]
	v_pk_mul_f32 v[234:235], v[16:17], v[8:9]
	v_pk_mul_f32 v[238:239], v[10:11], v[2:3]
	v_pk_mul_f32 v[242:243], v[12:13], v[4:5]
	v_pk_add_f32 v[228:229], v[228:229], v[248:249] op_sel_hi:[1,0]
	v_pk_add_f32 v[232:233], v[232:233], v[248:249] op_sel_hi:[1,0]
	v_pk_add_f32 v[236:237], v[236:237], v[248:249] op_sel_hi:[1,0]
	v_pk_add_f32 v[240:241], v[240:241], v[248:249] op_sel_hi:[1,0]
	v_rcp_f32_e32 v228, v228
	v_rcp_f32_e32 v229, v229
	v_rcp_f32_e32 v232, v232
	v_rcp_f32_e32 v233, v233
	v_rcp_f32_e32 v236, v236
	v_rcp_f32_e32 v237, v237
	v_rcp_f32_e32 v240, v240
	v_rcp_f32_e32 v241, v241
	v_pk_mul_f32 v[230:231], v[230:231], v[246:247] op_sel_hi:[1,0]
	v_pk_mul_f32 v[234:235], v[234:235], v[246:247] op_sel_hi:[1,0]
	v_pk_mul_f32 v[238:239], v[238:239], v[246:247] op_sel_hi:[1,0]
	v_pk_mul_f32 v[242:243], v[242:243], v[246:247] op_sel_hi:[1,0]
	v_pk_mul_f32 v[230:231], v[230:231], v[228:229]
	v_pk_mul_f32 v[234:235], v[234:235], v[232:233]
	v_pk_mul_f32 v[238:239], v[238:239], v[236:237]
	v_pk_mul_f32 v[242:243], v[242:243], v[240:241]
	v_cvt_pk_bf16_f32 v2, v230, v231
	v_cvt_pk_bf16_f32 v3, v234, v235
	v_cvt_pk_bf16_f32 v4, v238, v239
	v_cvt_pk_bf16_f32 v5, v242, v243
	global_store_dwordx4 v[18:19], v[2:5], off
	s_cbranch_vccnz .LBB0_199
	s_andn2_b64 vcc, exec, s[18:19]
	s_cbranch_vccnz .LBB0_198
	s_barrier
	s_branch .LBB0_198

; __device__ __forceinline__ unsigned cvt_pk_bf16(float lo, float hi) { unsigned r; asm volatile("v_cvt_pk_bf16_f32 %0, %1, %2" : "=v"(r) : "v"(lo), "v"(hi)); return r; }
; __device__ __forceinline__ float row_rstd(const float* rss, int row) { if (!rss) return 1.0f; const f32x4 s = *(const f32x4*)(rss + 4 * (size_t)row); return __builtin_amdgcn_rsqf(((s[0] + s[1]) + (s[2] + s[3])) * (1.0f / 1024.0f) + 1e-6f); }
;     __device__ __forceinline__ void operator()(const f32x4 (&acc)[2][2][4][2], const Unit& u, int wr, int wc, int fr, int fq) const {
;     ...
;             for (int m = 0; m < 4; ++m) { const int row = row0 + ai * HALF + m * 16; bf16_t* rowp = O + (size_t)row * ldc + col0; const float rs = row_rstd(rss, row);
; #pragma unroll
;                 for (int bj = 0; bj < 2; ++bj) { const f32x4 v0 = acc[ai][bj][m][0] * rs, v1 = acc[ai][bj][m][1] * rs;
;                     u32x4 w; w.x = cvt_pk_bf16(v0[0], v0[1]); w.y = cvt_pk_bf16(v0[2], v0[3]); w.z = cvt_pk_bf16(v1[0], v1[1]); w.w = cvt_pk_bf16(v1[2], v1[3]);
;                     *(u32x4*)(rowp + bj * HALF) = w; } }
.LBB0_409:
	v_lshl_or_b32 v146, s65, 8, v151
	v_lshl_add_u32 v148, s66, 8, v1
	v_add_u32_e32 v190, 0, v148
	v_ashrrev_i32_e32 v191, 31, v190
	v_lshl_add_u64 v[190:191], v[190:191], 4, s[24:25]
	global_load_dwordx4 v[190:193], v[190:191], off
	v_add_u32_e32 v194, 16, v148
	v_ashrrev_i32_e32 v195, 31, v194
	v_lshl_add_u64 v[194:195], v[194:195], 4, s[24:25]
	global_load_dwordx4 v[194:197], v[194:195], off
	v_add_u32_e32 v198, 32, v148
	v_ashrrev_i32_e32 v199, 31, v198
	v_lshl_add_u64 v[198:199], v[198:199], 4, s[24:25]
	global_load_dwordx4 v[198:201], v[198:199], off
	v_add_u32_e32 v202, 48, v148
	v_ashrrev_i32_e32 v203, 31, v202
	v_lshl_add_u64 v[202:203], v[202:203], 4, s[24:25]
	global_load_dwordx4 v[202:205], v[202:203], off
	v_add_u32_e32 v206, 128, v148
	v_ashrrev_i32_e32 v207, 31, v206
	v_lshl_add_u64 v[206:207], v[206:207], 4, s[24:25]
	global_load_dwordx4 v[206:209], v[206:207], off
	v_add_u32_e32 v210, 144, v148
	v_ashrrev_i32_e32 v211, 31, v210
	v_lshl_add_u64 v[210:211], v[210:211], 4, s[24:25]
	global_load_dwordx4 v[210:213], v[210:211], off
	v_add_u32_e32 v214, 160, v148
	v_ashrrev_i32_e32 v215, 31, v214
	v_lshl_add_u64 v[214:215], v[214:215], 4, s[24:25]
	global_load_dwordx4 v[214:217], v[214:215], off
	v_add_u32_e32 v218, 176, v148
	v_ashrrev_i32_e32 v219, 31, v218
	v_lshl_add_u64 v[218:219], v[218:219], 4, s[24:25]
	global_load_dwordx4 v[218:221], v[218:219], off
	v_ashrrev_i32_e32 v147, 31, v146
	v_mov_b64_e32 v[144:145], s[22:23]
	v_ashrrev_i32_e32 v149, 31, v148
	v_mad_i64_i32 v[160:161], s[6:7], v148, s62, v[144:145]
	v_lshlrev_b64 v[146:147], 1, v[146:147]
	v_lshl_add_u64 v[164:165], v[160:161], 0, v[146:147]
	v_lshl_add_u64 v[160:161], v[148:149], 4, s[24:25]
	s_mov_b64 s[34:35], -1
	s_and_b64 vcc, exec, s[8:9]
	s_waitcnt vmcnt(7)
	v_mov_b64_e32 v[160:161], v[190:191]
	v_mov_b64_e32 v[162:163], v[192:193]
	v_mov_b32_e32 v166, v161
	v_mov_b32_e32 v167, v162
	v_mov_b32_e32 v161, v163
	v_pk_add_f32 v[160:161], v[166:167], v[160:161]
	s_nop 0
	v_add_f32_e32 v149, v160, v161
	v_fmamk_f32 v149, v149, 0x3a800000, v138
	v_rsq_f32_e32 v160, v149
	s_nop 0
	v_pk_mul_f32 v[122:123], v[122:123], v[160:161] op_sel_hi:[1,0]
	v_pk_mul_f32 v[124:125], v[124:125], v[160:161] op_sel_hi:[1,0]
	v_cvt_pk_bf16_f32 v122, v122, v123
	v_pk_mul_f32 v[128:129], v[128:129], v[160:161] op_sel_hi:[1,0]
	v_cvt_pk_bf16_f32 v123, v124, v125
	v_pk_mul_f32 v[126:127], v[126:127], v[160:161] op_sel_hi:[1,0]
	v_pk_mul_f32 v[118:119], v[118:119], v[160:161] op_sel_hi:[1,0]
	v_cvt_pk_bf16_f32 v124, v126, v127
	v_cvt_pk_bf16_f32 v125, v128, v129
	global_store_dwordx4 v[164:165], v[122:125], off
	v_pk_mul_f32 v[120:121], v[120:121], v[160:161] op_sel_hi:[1,0]
	s_nop 0
	v_pk_mul_f32 v[122:123], v[116:117], v[160:161] op_sel_hi:[1,0]
	v_pk_mul_f32 v[116:117], v[114:115], v[160:161] op_sel_hi:[1,0]
	v_cvt_pk_bf16_f32 v114, v118, v119
	v_cvt_pk_bf16_f32 v115, v120, v121
	s_nop 0
	v_cvt_pk_bf16_f32 v116, v116, v117
	v_cvt_pk_bf16_f32 v117, v122, v123
	global_store_dwordx4 v[164:165], v[114:117], off offset:256
	s_nop 1
	v_or_b32_e32 v114, 16, v148
	v_ashrrev_i32_e32 v115, 31, v114
	v_mad_i64_i32 v[116:117], s[6:7], v114, s62, v[144:145]
	v_lshl_add_u64 v[114:115], v[114:115], 4, s[24:25]
	v_lshl_add_u64 v[118:119], v[116:117], 0, v[146:147]
	s_waitcnt vmcnt(8)
	v_mov_b64_e32 v[114:115], v[194:195]
	v_mov_b64_e32 v[116:117], v[196:197]
	v_mov_b32_e32 v120, v115
	v_mov_b32_e32 v121, v116
	v_mov_b32_e32 v115, v117
	v_pk_add_f32 v[114:115], v[120:121], v[114:115]
	s_nop 0
	v_add_f32_e32 v114, v114, v115
	v_fmamk_f32 v114, v114, 0x3a800000, v138
	v_rsq_f32_e32 v114, v114
	s_nop 0
	v_pk_mul_f32 v[112:113], v[112:113], v[114:115] op_sel_hi:[1,0]
	v_pk_mul_f32 v[110:111], v[110:111], v[114:115] op_sel_hi:[1,0]
	v_pk_mul_f32 v[116:117], v[108:109], v[114:115] op_sel_hi:[1,0]
	v_pk_mul_f32 v[108:109], v[106:107], v[114:115] op_sel_hi:[1,0]
	v_cvt_pk_bf16_f32 v106, v110, v111
	v_cvt_pk_bf16_f32 v107, v112, v113
	v_pk_mul_f32 v[102:103], v[102:103], v[114:115] op_sel_hi:[1,0]
	v_cvt_pk_bf16_f32 v108, v108, v109
	v_cvt_pk_bf16_f32 v109, v116, v117
	global_store_dwordx4 v[118:119], v[106:109], off
	v_pk_mul_f32 v[104:105], v[104:105], v[114:115] op_sel_hi:[1,0]
	s_nop 0
	v_pk_mul_f32 v[106:107], v[100:101], v[114:115] op_sel_hi:[1,0]
	v_pk_mul_f32 v[100:101], v[98:99], v[114:115] op_sel_hi:[1,0]
	v_cvt_pk_bf16_f32 v98, v102, v103
	v_cvt_pk_bf16_f32 v99, v104, v105
	s_nop 0
	v_cvt_pk_bf16_f32 v100, v100, v101
	v_cvt_pk_bf16_f32 v101, v106, v107
	global_store_dwordx4 v[118:119], v[98:101], off offset:256
	s_nop 1
	v_or_b32_e32 v98, 32, v148
	v_ashrrev_i32_e32 v99, 31, v98
	v_mad_i64_i32 v[100:101], s[6:7], v98, s62, v[144:145]
	v_lshl_add_u64 v[98:99], v[98:99], 4, s[24:25]
	v_lshl_add_u64 v[102:103], v[100:101], 0, v[146:147]
	s_waitcnt vmcnt(9)
	v_mov_b64_e32 v[98:99], v[198:199]
	v_mov_b64_e32 v[100:101], v[200:201]
	v_mov_b32_e32 v104, v99
	v_mov_b32_e32 v105, v100
	v_mov_b32_e32 v99, v101
	v_pk_add_f32 v[98:99], v[104:105], v[98:99]
	s_nop 0
	v_add_f32_e32 v98, v98, v99
	v_fmamk_f32 v98, v98, 0x3a800000, v138
	v_rsq_f32_e32 v98, v98
	s_nop 0
	v_pk_mul_f32 v[96:97], v[96:97], v[98:99] op_sel_hi:[1,0]
	v_pk_mul_f32 v[94:95], v[94:95], v[98:99] op_sel_hi:[1,0]
	v_pk_mul_f32 v[100:101], v[92:93], v[98:99] op_sel_hi:[1,0]
	v_pk_mul_f32 v[92:93], v[90:91], v[98:99] op_sel_hi:[1,0]
	v_cvt_pk_bf16_f32 v90, v94, v95
	v_cvt_pk_bf16_f32 v91, v96, v97
	v_pk_mul_f32 v[86:87], v[86:87], v[98:99] op_sel_hi:[1,0]
	v_cvt_pk_bf16_f32 v92, v92, v93
	v_cvt_pk_bf16_f32 v93, v100, v101
	global_store_dwordx4 v[102:103], v[90:93], off
	v_pk_mul_f32 v[88:89], v[88:89], v[98:99] op_sel_hi:[1,0]
	s_nop 0
	v_pk_mul_f32 v[90:91], v[84:85], v[98:99] op_sel_hi:[1,0]
	v_pk_mul_f32 v[84:85], v[82:83], v[98:99] op_sel_hi:[1,0]
	v_cvt_pk_bf16_f32 v82, v86, v87
	v_cvt_pk_bf16_f32 v83, v88, v89
	s_nop 0
	v_cvt_pk_bf16_f32 v84, v84, v85
	v_cvt_pk_bf16_f32 v85, v90, v91
	global_store_dwordx4 v[102:103], v[82:85], off offset:256
	s_nop 1
	v_or_b32_e32 v82, 48, v148
	v_ashrrev_i32_e32 v83, 31, v82
	v_mad_i64_i32 v[84:85], s[6:7], v82, s62, v[144:145]
	v_lshl_add_u64 v[82:83], v[82:83], 4, s[24:25]
	v_lshl_add_u64 v[86:87], v[84:85], 0, v[146:147]
	s_waitcnt vmcnt(10)
; __device__ __forceinline__ unsigned cvt_pk_bf16(float lo, float hi) { unsigned r; asm volatile("v_cvt_pk_bf16_f32 %0, %1, %2" : "=v"(r) : "v"(lo), "v"(hi)); return r; }
; __device__ __forceinline__ float row_rstd(const float* rss, int row) { if (!rss) return 1.0f; const f32x4 s = *(const f32x4*)(rss + 4 * (size_t)row); return __builtin_amdgcn_rsqf(((s[0] + s[1]) + (s[2] + s[3])) * (1.0f / 1024.0f) + 1e-6f); }
;     __device__ __forceinline__ void operator()(const f32x4 (&acc)[2][2][4][2], const Unit& u, int wr, int wc, int fr, int fq) const {
;     ...
;             for (int m = 0; m < 4; ++m) { const int row = row0 + ai * HALF + m * 16; bf16_t* rowp = O + (size_t)row * ldc + col0; const float rs = row_rstd(rss, row);
; #pragma unroll
;                 for (int bj = 0; bj < 2; ++bj) { const f32x4 v0 = acc[ai][bj][m][0] * rs, v1 = acc[ai][bj][m][1] * rs;
;                     u32x4 w; w.x = cvt_pk_bf16(v0[0], v0[1]); w.y = cvt_pk_bf16(v0[2], v0[3]); w.z = cvt_pk_bf16(v1[0], v1[1]); w.w = cvt_pk_bf16(v1[2], v1[3]);
;                     *(u32x4*)(rowp + bj * HALF) = w; } }
	v_mov_b64_e32 v[82:83], v[202:203]
	v_mov_b64_e32 v[84:85], v[204:205]
	v_mov_b32_e32 v88, v83
	v_mov_b32_e32 v89, v84
	v_mov_b32_e32 v83, v85
	v_pk_add_f32 v[82:83], v[88:89], v[82:83]
	s_nop 0
	v_add_f32_e32 v82, v82, v83
	v_fmamk_f32 v82, v82, 0x3a800000, v138
	v_rsq_f32_e32 v82, v82
	s_nop 0
	v_pk_mul_f32 v[80:81], v[80:81], v[82:83] op_sel_hi:[1,0]
	v_pk_mul_f32 v[78:79], v[78:79], v[82:83] op_sel_hi:[1,0]
	v_pk_mul_f32 v[84:85], v[76:77], v[82:83] op_sel_hi:[1,0]
	v_pk_mul_f32 v[76:77], v[74:75], v[82:83] op_sel_hi:[1,0]
	v_cvt_pk_bf16_f32 v74, v78, v79
	v_cvt_pk_bf16_f32 v75, v80, v81
	v_pk_mul_f32 v[70:71], v[70:71], v[82:83] op_sel_hi:[1,0]
	v_cvt_pk_bf16_f32 v76, v76, v77
	v_cvt_pk_bf16_f32 v77, v84, v85
	global_store_dwordx4 v[86:87], v[74:77], off
	v_pk_mul_f32 v[72:73], v[72:73], v[82:83] op_sel_hi:[1,0]
	s_nop 0
	v_pk_mul_f32 v[74:75], v[68:69], v[82:83] op_sel_hi:[1,0]
	v_pk_mul_f32 v[68:69], v[66:67], v[82:83] op_sel_hi:[1,0]
	v_cvt_pk_bf16_f32 v66, v70, v71
	v_cvt_pk_bf16_f32 v67, v72, v73
	s_nop 0
	v_cvt_pk_bf16_f32 v68, v68, v69
	v_cvt_pk_bf16_f32 v69, v74, v75
	global_store_dwordx4 v[86:87], v[66:69], off offset:256
	s_nop 1
	v_add_u32_e32 v66, 0x80, v148
	v_ashrrev_i32_e32 v67, 31, v66
	v_mad_i64_i32 v[68:69], s[6:7], v66, s62, v[144:145]
	v_lshl_add_u64 v[66:67], v[66:67], 4, s[24:25]
	v_lshl_add_u64 v[70:71], v[68:69], 0, v[146:147]
	s_waitcnt vmcnt(11)
	v_mov_b64_e32 v[66:67], v[206:207]
	v_mov_b64_e32 v[68:69], v[208:209]
	v_mov_b32_e32 v72, v67
	v_mov_b32_e32 v73, v68
	v_mov_b32_e32 v67, v69
	v_pk_add_f32 v[66:67], v[72:73], v[66:67]
	s_nop 0
	v_add_f32_e32 v66, v66, v67
	v_fmamk_f32 v66, v66, 0x3a800000, v138
	v_rsq_f32_e32 v66, v66
	s_nop 0
	v_pk_mul_f32 v[64:65], v[64:65], v[66:67] op_sel_hi:[1,0]
	v_pk_mul_f32 v[62:63], v[62:63], v[66:67] op_sel_hi:[1,0]
	v_pk_mul_f32 v[68:69], v[60:61], v[66:67] op_sel_hi:[1,0]
	v_pk_mul_f32 v[60:61], v[58:59], v[66:67] op_sel_hi:[1,0]
	v_cvt_pk_bf16_f32 v58, v62, v63
	v_cvt_pk_bf16_f32 v59, v64, v65
	v_pk_mul_f32 v[54:55], v[54:55], v[66:67] op_sel_hi:[1,0]
	v_cvt_pk_bf16_f32 v60, v60, v61
	v_cvt_pk_bf16_f32 v61, v68, v69
	global_store_dwordx4 v[70:71], v[58:61], off
	v_pk_mul_f32 v[56:57], v[56:57], v[66:67] op_sel_hi:[1,0]
	s_nop 0
	v_pk_mul_f32 v[58:59], v[52:53], v[66:67] op_sel_hi:[1,0]
	v_pk_mul_f32 v[52:53], v[50:51], v[66:67] op_sel_hi:[1,0]
	v_cvt_pk_bf16_f32 v50, v54, v55
	v_cvt_pk_bf16_f32 v51, v56, v57
	s_nop 0
	v_cvt_pk_bf16_f32 v52, v52, v53
	v_cvt_pk_bf16_f32 v53, v58, v59
	global_store_dwordx4 v[70:71], v[50:53], off offset:256
	s_nop 1
	v_add_u32_e32 v50, 0x90, v148
	v_ashrrev_i32_e32 v51, 31, v50
	v_mad_i64_i32 v[52:53], s[6:7], v50, s62, v[144:145]
	v_lshl_add_u64 v[50:51], v[50:51], 4, s[24:25]
	v_lshl_add_u64 v[54:55], v[52:53], 0, v[146:147]
	s_waitcnt vmcnt(12)
	v_mov_b64_e32 v[50:51], v[210:211]
	v_mov_b64_e32 v[52:53], v[212:213]
	v_mov_b32_e32 v56, v51
	v_mov_b32_e32 v57, v52
	v_mov_b32_e32 v51, v53
	v_pk_add_f32 v[50:51], v[56:57], v[50:51]
	s_nop 0
	v_add_f32_e32 v50, v50, v51
	v_fmamk_f32 v50, v50, 0x3a800000, v138
	v_rsq_f32_e32 v50, v50
	s_nop 0
	v_pk_mul_f32 v[48:49], v[48:49], v[50:51] op_sel_hi:[1,0]
	v_pk_mul_f32 v[46:47], v[46:47], v[50:51] op_sel_hi:[1,0]
	v_pk_mul_f32 v[52:53], v[44:45], v[50:51] op_sel_hi:[1,0]
	v_pk_mul_f32 v[44:45], v[42:43], v[50:51] op_sel_hi:[1,0]
	v_cvt_pk_bf16_f32 v42, v46, v47
	v_cvt_pk_bf16_f32 v43, v48, v49
	v_pk_mul_f32 v[38:39], v[38:39], v[50:51] op_sel_hi:[1,0]
	v_cvt_pk_bf16_f32 v44, v44, v45
	v_cvt_pk_bf16_f32 v45, v52, v53
	global_store_dwordx4 v[54:55], v[42:45], off
	v_pk_mul_f32 v[40:41], v[40:41], v[50:51] op_sel_hi:[1,0]
	s_nop 0
	v_pk_mul_f32 v[42:43], v[36:37], v[50:51] op_sel_hi:[1,0]
	v_pk_mul_f32 v[36:37], v[34:35], v[50:51] op_sel_hi:[1,0]
	v_cvt_pk_bf16_f32 v34, v38, v39
	v_cvt_pk_bf16_f32 v35, v40, v41
	s_nop 0
	v_cvt_pk_bf16_f32 v36, v36, v37
	v_cvt_pk_bf16_f32 v37, v42, v43
	global_store_dwordx4 v[54:55], v[34:37], off offset:256
	s_nop 1
	v_add_u32_e32 v34, 0xa0, v148
	v_ashrrev_i32_e32 v35, 31, v34
	v_mad_i64_i32 v[36:37], s[6:7], v34, s62, v[144:145]
	v_lshl_add_u64 v[34:35], v[34:35], 4, s[24:25]
	v_lshl_add_u64 v[38:39], v[36:37], 0, v[146:147]
	s_waitcnt vmcnt(13)
	v_mov_b64_e32 v[34:35], v[214:215]
	v_mov_b64_e32 v[36:37], v[216:217]
	v_mov_b32_e32 v40, v35
	v_mov_b32_e32 v41, v36
	v_mov_b32_e32 v35, v37
	v_pk_add_f32 v[34:35], v[40:41], v[34:35]
	s_nop 0
	v_add_f32_e32 v34, v34, v35
	v_fmamk_f32 v34, v34, 0x3a800000, v138
	v_rsq_f32_e32 v34, v34
	s_nop 0
	v_pk_mul_f32 v[32:33], v[32:33], v[34:35] op_sel_hi:[1,0]
	v_pk_mul_f32 v[30:31], v[30:31], v[34:35] op_sel_hi:[1,0]
	v_pk_mul_f32 v[36:37], v[28:29], v[34:35] op_sel_hi:[1,0]
	v_pk_mul_f32 v[28:29], v[26:27], v[34:35] op_sel_hi:[1,0]
	v_cvt_pk_bf16_f32 v26, v30, v31
	v_cvt_pk_bf16_f32 v27, v32, v33
	v_pk_mul_f32 v[22:23], v[22:23], v[34:35] op_sel_hi:[1,0]
	v_cvt_pk_bf16_f32 v28, v28, v29
	v_cvt_pk_bf16_f32 v29, v36, v37
	global_store_dwordx4 v[38:39], v[26:29], off
	v_pk_mul_f32 v[24:25], v[24:25], v[34:35] op_sel_hi:[1,0]
	s_nop 0
	v_pk_mul_f32 v[26:27], v[20:21], v[34:35] op_sel_hi:[1,0]
	v_pk_mul_f32 v[20:21], v[18:19], v[34:35] op_sel_hi:[1,0]
	v_cvt_pk_bf16_f32 v18, v22, v23
	v_add_u32_e32 v22, 0xb0, v148
	v_cvt_pk_bf16_f32 v19, v24, v25
	v_ashrrev_i32_e32 v23, 31, v22
	v_cvt_pk_bf16_f32 v20, v20, v21
	v_cvt_pk_bf16_f32 v21, v26, v27
	global_store_dwordx4 v[38:39], v[18:21], off offset:256
	s_nop 1
	v_lshl_add_u64 v[18:19], v[22:23], 4, s[24:25]
	s_waitcnt vmcnt(14)
	v_mov_b64_e32 v[18:19], v[218:219]
	v_mov_b64_e32 v[20:21], v[220:221]
	v_mov_b32_e32 v24, v19
	v_mov_b32_e32 v25, v20
	v_mov_b32_e32 v19, v21
	v_pk_add_f32 v[18:19], v[24:25], v[18:19]
	v_mad_i64_i32 v[20:21], s[6:7], v22, s62, v[144:145]
	v_add_f32_e32 v18, v18, v19
	v_fmamk_f32 v18, v18, 0x3a800000, v138
	v_rsq_f32_e32 v18, v18
	v_lshl_add_u64 v[20:21], v[20:21], 0, v[146:147]
	v_pk_mul_f32 v[16:17], v[16:17], v[18:19] op_sel_hi:[1,0]
	v_pk_mul_f32 v[14:15], v[14:15], v[18:19] op_sel_hi:[1,0]
	v_pk_mul_f32 v[22:23], v[12:13], v[18:19] op_sel_hi:[1,0]
	v_pk_mul_f32 v[12:13], v[10:11], v[18:19] op_sel_hi:[1,0]
	v_cvt_pk_bf16_f32 v10, v14, v15
	v_cvt_pk_bf16_f32 v11, v16, v17
	v_pk_mul_f32 v[8:9], v[8:9], v[18:19] op_sel_hi:[1,0]
	v_cvt_pk_bf16_f32 v12, v12, v13
	v_cvt_pk_bf16_f32 v13, v22, v23
	global_store_dwordx4 v[20:21], v[10:13], off
	v_pk_mul_f32 v[6:7], v[6:7], v[18:19] op_sel_hi:[1,0]
	s_nop 0
	v_pk_mul_f32 v[10:11], v[4:5], v[18:19] op_sel_hi:[1,0]
	v_pk_mul_f32 v[4:5], v[2:3], v[18:19] op_sel_hi:[1,0]
	v_cvt_pk_bf16_f32 v2, v6, v7
	v_cvt_pk_bf16_f32 v3, v8, v9
	s_nop 0
	v_cvt_pk_bf16_f32 v4, v4, v5
	v_cvt_pk_bf16_f32 v5, v10, v11
	global_store_dwordx4 v[20:21], v[2:5], off offset:256
	s_cbranch_vccnz .LBB0_397
	s_andn2_b64 vcc, exec, s[20:21]
	s_cbranch_vccnz .LBB0_396
	s_barrier
	s_branch .LBB0_396

; __device__ __forceinline__ unsigned cvt_pk_bf16(float lo, float hi) { unsigned r; asm volatile("v_cvt_pk_bf16_f32 %0, %1, %2" : "=v"(r) : "v"(lo), "v"(hi)); return r; }
; __device__ __forceinline__ float silu_f(float g) { return g * __builtin_amdgcn_rcpf(1.0f + __expf(-g)); }
; __device__ __forceinline__ float row_rstd(const float* rss, int row) { if (!rss) return 1.0f; const f32x4 s = *(const f32x4*)(rss + 4 * (size_t)row); return __builtin_amdgcn_rsqf(((s[0] + s[1]) + (s[2] + s[3])) * (1.0f / 1024.0f) + 1e-6f); }
;     __device__ __forceinline__ void operator()(const f32x4 (&acc)[2][2][4][2], const Unit& u, int wr, int wc, int fr, int fq) const {
;     ...
;             for (int m = 0; m < 4; ++m) { const int row = row0 + ai * HALF + m * 16; bf16_t* rowp = O + (size_t)row * ldc + col0; const float rs = row_rstd(rss, row);
;                 const f32x4 g0 = acc[ai][0][m][0] * rs, g1 = acc[ai][0][m][1] * rs, u0 = acc[ai][1][m][0] * rs, u1 = acc[ai][1][m][1] * rs;
;                 u32x4 w;
;                 w.x = cvt_pk_bf16(silu_f(g0[0]) * u0[0], silu_f(g0[1]) * u0[1]); w.y = cvt_pk_bf16(silu_f(g0[2]) * u0[2], silu_f(g0[3]) * u0[3]);
;                 w.z = cvt_pk_bf16(silu_f(g1[0]) * u1[0], silu_f(g1[1]) * u1[1]); w.w = cvt_pk_bf16(silu_f(g1[2]) * u1[2], silu_f(g1[3]) * u1[3]);
;                 *(u32x4*)rowp = w; }
.LBB0_1133:
	v_lshl_or_b32 v146, s0, 7, v151
	v_lshl_add_u32 v148, s1, 8, v1
	v_add_u32_e32 v190, 0, v148
	v_ashrrev_i32_e32 v191, 31, v190
	v_lshl_add_u64 v[190:191], v[190:191], 4, s[24:25]
	global_load_dwordx4 v[190:193], v[190:191], off
	v_add_u32_e32 v194, 16, v148
	v_ashrrev_i32_e32 v195, 31, v194
	v_lshl_add_u64 v[194:195], v[194:195], 4, s[24:25]
	global_load_dwordx4 v[194:197], v[194:195], off
	v_add_u32_e32 v198, 32, v148
	v_ashrrev_i32_e32 v199, 31, v198
	v_lshl_add_u64 v[198:199], v[198:199], 4, s[24:25]
	global_load_dwordx4 v[198:201], v[198:199], off
	v_add_u32_e32 v202, 48, v148
	v_ashrrev_i32_e32 v203, 31, v202
	v_lshl_add_u64 v[202:203], v[202:203], 4, s[24:25]
	global_load_dwordx4 v[202:205], v[202:203], off
	v_add_u32_e32 v206, 128, v148
	v_ashrrev_i32_e32 v207, 31, v206
	v_lshl_add_u64 v[206:207], v[206:207], 4, s[24:25]
	global_load_dwordx4 v[206:209], v[206:207], off
	v_add_u32_e32 v210, 144, v148
	v_ashrrev_i32_e32 v211, 31, v210
	v_lshl_add_u64 v[210:211], v[210:211], 4, s[24:25]
	global_load_dwordx4 v[210:213], v[210:211], off
	v_add_u32_e32 v214, 160, v148
	v_ashrrev_i32_e32 v215, 31, v214
	v_lshl_add_u64 v[214:215], v[214:215], 4, s[24:25]
	global_load_dwordx4 v[214:217], v[214:215], off
	v_add_u32_e32 v218, 176, v148
	v_ashrrev_i32_e32 v219, 31, v218
	v_lshl_add_u64 v[218:219], v[218:219], 4, s[24:25]
	global_load_dwordx4 v[218:221], v[218:219], off
	v_ashrrev_i32_e32 v147, 31, v146
	v_mov_b64_e32 v[144:145], s[22:23]
	v_ashrrev_i32_e32 v149, 31, v148
	v_mad_i64_i32 v[160:161], s[0:1], v148, s4, v[144:145]
	v_lshlrev_b64 v[146:147], 1, v[146:147]
	v_lshl_add_u64 v[164:165], v[160:161], 0, v[146:147]
	v_lshl_add_u64 v[160:161], v[148:149], 4, s[24:25]
	s_mov_b64 s[34:35], -1
	s_and_b64 vcc, exec, s[8:9]
	s_waitcnt vmcnt(7)
	v_mov_b64_e32 v[160:161], v[190:191]
	v_mov_b64_e32 v[162:163], v[192:193]
	v_mov_b32_e32 v166, v161
	v_mov_b32_e32 v167, v162
	v_mov_b32_e32 v161, v163
	v_pk_add_f32 v[160:161], v[166:167], v[160:161]
	s_nop 0
	v_add_f32_e32 v149, v160, v161
	v_fmamk_f32 v149, v149, 0x3a800000, v138
	v_rsq_f32_e32 v160, v149
	s_nop 0
	v_mul_f32_e32 v244, 0xbfb8aa3b, v160
	v_mul_f32_e32 v246, v160, v160
	v_mov_b32_e32 v248, 1.0
	v_pk_mul_f32 v[228:229], v[122:123], v[244:245] op_sel_hi:[1,0]
	v_pk_mul_f32 v[232:233], v[124:125], v[244:245] op_sel_hi:[1,0]
	v_pk_mul_f32 v[236:237], v[126:127], v[244:245] op_sel_hi:[1,0]
	v_pk_mul_f32 v[240:241], v[128:129], v[244:245] op_sel_hi:[1,0]
	v_exp_f32_e32 v228, v228
	v_exp_f32_e32 v229, v229
	v_exp_f32_e32 v232, v232
	v_exp_f32_e32 v233, v233
	v_exp_f32_e32 v236, v236
	v_exp_f32_e32 v237, v237
	v_exp_f32_e32 v240, v240
	v_exp_f32_e32 v241, v241
	v_pk_mul_f32 v[230:231], v[122:123], v[118:119]
	v_pk_mul_f32 v[234:235], v[124:125], v[120:121]
	v_pk_mul_f32 v[238:239], v[126:127], v[114:115]
	v_pk_mul_f32 v[242:243], v[128:129], v[116:117]
	v_pk_add_f32 v[228:229], v[228:229], v[248:249] op_sel_hi:[1,0]
	v_pk_add_f32 v[232:233], v[232:233], v[248:249] op_sel_hi:[1,0]
	v_pk_add_f32 v[236:237], v[236:237], v[248:249] op_sel_hi:[1,0]
	v_pk_add_f32 v[240:241], v[240:241], v[248:249] op_sel_hi:[1,0]
	v_rcp_f32_e32 v228, v228
	v_rcp_f32_e32 v229, v229
	v_rcp_f32_e32 v232, v232
	v_rcp_f32_e32 v233, v233
	v_rcp_f32_e32 v236, v236
	v_rcp_f32_e32 v237, v237
	v_rcp_f32_e32 v240, v240
	v_rcp_f32_e32 v241, v241
	v_pk_mul_f32 v[230:231], v[230:231], v[246:247] op_sel_hi:[1,0]
	v_pk_mul_f32 v[234:235], v[234:235], v[246:247] op_sel_hi:[1,0]
	v_pk_mul_f32 v[238:239], v[238:239], v[246:247] op_sel_hi:[1,0]
	v_pk_mul_f32 v[242:243], v[242:243], v[246:247] op_sel_hi:[1,0]
	v_pk_mul_f32 v[230:231], v[230:231], v[228:229]
	v_pk_mul_f32 v[234:235], v[234:235], v[232:233]
	v_pk_mul_f32 v[238:239], v[238:239], v[236:237]
	v_pk_mul_f32 v[242:243], v[242:243], v[240:241]
	v_cvt_pk_bf16_f32 v114, v230, v231
	v_cvt_pk_bf16_f32 v115, v234, v235
	v_cvt_pk_bf16_f32 v116, v238, v239
	v_cvt_pk_bf16_f32 v117, v242, v243
	global_store_dwordx4 v[164:165], v[114:117], off
	s_nop 1
	v_or_b32_e32 v116, 16, v148
	v_ashrrev_i32_e32 v117, 31, v116
	v_mad_i64_i32 v[114:115], s[0:1], v116, s4, v[144:145]
	v_lshl_add_u64 v[116:117], v[116:117], 4, s[24:25]
	v_lshl_add_u64 v[114:115], v[114:115], 0, v[146:147]
	s_waitcnt vmcnt(7)
	v_mov_b64_e32 v[116:117], v[194:195]
	v_mov_b64_e32 v[118:119], v[196:197]
	v_mov_b32_e32 v120, v117
	v_mov_b32_e32 v121, v118
	v_mov_b32_e32 v117, v119
	v_pk_add_f32 v[116:117], v[120:121], v[116:117]
	s_nop 0
	v_add_f32_e32 v116, v116, v117
	v_fmamk_f32 v116, v116, 0x3a800000, v138
	v_rsq_f32_e32 v116, v116
	s_nop 0
	v_mul_f32_e32 v244, 0xbfb8aa3b, v116
	v_mul_f32_e32 v246, v116, v116
	v_mov_b32_e32 v248, 1.0
	v_pk_mul_f32 v[228:229], v[110:111], v[244:245] op_sel_hi:[1,0]
	v_pk_mul_f32 v[232:233], v[112:113], v[244:245] op_sel_hi:[1,0]
	v_pk_mul_f32 v[236:237], v[106:107], v[244:245] op_sel_hi:[1,0]
	v_pk_mul_f32 v[240:241], v[108:109], v[244:245] op_sel_hi:[1,0]
	v_exp_f32_e32 v228, v228
	v_exp_f32_e32 v229, v229
	v_exp_f32_e32 v232, v232
	v_exp_f32_e32 v233, v233
	v_exp_f32_e32 v236, v236
	v_exp_f32_e32 v237, v237
	v_exp_f32_e32 v240, v240
	v_exp_f32_e32 v241, v241
	v_pk_mul_f32 v[230:231], v[110:111], v[102:103]
	v_pk_mul_f32 v[234:235], v[112:113], v[104:105]
	v_pk_mul_f32 v[238:239], v[106:107], v[98:99]
	v_pk_mul_f32 v[242:243], v[108:109], v[100:101]
	v_pk_add_f32 v[228:229], v[228:229], v[248:249] op_sel_hi:[1,0]
	v_pk_add_f32 v[232:233], v[232:233], v[248:249] op_sel_hi:[1,0]
	v_pk_add_f32 v[236:237], v[236:237], v[248:249] op_sel_hi:[1,0]
	v_pk_add_f32 v[240:241], v[240:241], v[248:249] op_sel_hi:[1,0]
	v_rcp_f32_e32 v228, v228
	v_rcp_f32_e32 v229, v229
	v_rcp_f32_e32 v232, v232
	v_rcp_f32_e32 v233, v233
	v_rcp_f32_e32 v236, v236
	v_rcp_f32_e32 v237, v237
	v_rcp_f32_e32 v240, v240
	v_rcp_f32_e32 v241, v241
	v_pk_mul_f32 v[230:231], v[230:231], v[246:247] op_sel_hi:[1,0]
	v_pk_mul_f32 v[234:235], v[234:235], v[246:247] op_sel_hi:[1,0]
	v_pk_mul_f32 v[238:239], v[238:239], v[246:247] op_sel_hi:[1,0]
	v_pk_mul_f32 v[242:243], v[242:243], v[246:247] op_sel_hi:[1,0]
	v_pk_mul_f32 v[230:231], v[230:231], v[228:229]
	v_pk_mul_f32 v[234:235], v[234:235], v[232:233]
	v_pk_mul_f32 v[238:239], v[238:239], v[236:237]
	v_pk_mul_f32 v[242:243], v[242:243], v[240:241]
	v_cvt_pk_bf16_f32 v98, v230, v231
	v_cvt_pk_bf16_f32 v99, v234, v235
	v_cvt_pk_bf16_f32 v100, v238, v239
	v_cvt_pk_bf16_f32 v101, v242, v243
	global_store_dwordx4 v[114:115], v[98:101], off
	s_nop 1
	v_or_b32_e32 v100, 32, v148
	v_ashrrev_i32_e32 v101, 31, v100
	v_mad_i64_i32 v[98:99], s[0:1], v100, s4, v[144:145]
	v_lshl_add_u64 v[100:101], v[100:101], 4, s[24:25]
	v_lshl_add_u64 v[98:99], v[98:99], 0, v[146:147]
	s_waitcnt vmcnt(7)
; __device__ __forceinline__ unsigned cvt_pk_bf16(float lo, float hi) { unsigned r; asm volatile("v_cvt_pk_bf16_f32 %0, %1, %2" : "=v"(r) : "v"(lo), "v"(hi)); return r; }
; __device__ __forceinline__ float silu_f(float g) { return g * __builtin_amdgcn_rcpf(1.0f + __expf(-g)); }
; __device__ __forceinline__ float row_rstd(const float* rss, int row) { if (!rss) return 1.0f; const f32x4 s = *(const f32x4*)(rss + 4 * (size_t)row); return __builtin_amdgcn_rsqf(((s[0] + s[1]) + (s[2] + s[3])) * (1.0f / 1024.0f) + 1e-6f); }
;     __device__ __forceinline__ void operator()(const f32x4 (&acc)[2][2][4][2], const Unit& u, int wr, int wc, int fr, int fq) const {
;     ...
;             for (int m = 0; m < 4; ++m) { const int row = row0 + ai * HALF + m * 16; bf16_t* rowp = O + (size_t)row * ldc + col0; const float rs = row_rstd(rss, row);
;                 const f32x4 g0 = acc[ai][0][m][0] * rs, g1 = acc[ai][0][m][1] * rs, u0 = acc[ai][1][m][0] * rs, u1 = acc[ai][1][m][1] * rs;
;                 u32x4 w;
;                 w.x = cvt_pk_bf16(silu_f(g0[0]) * u0[0], silu_f(g0[1]) * u0[1]); w.y = cvt_pk_bf16(silu_f(g0[2]) * u0[2], silu_f(g0[3]) * u0[3]);
;                 w.z = cvt_pk_bf16(silu_f(g1[0]) * u1[0], silu_f(g1[1]) * u1[1]); w.w = cvt_pk_bf16(silu_f(g1[2]) * u1[2], silu_f(g1[3]) * u1[3]);
;                 *(u32x4*)rowp = w; }
	v_mov_b64_e32 v[100:101], v[198:199]
	v_mov_b64_e32 v[102:103], v[200:201]
	v_mov_b32_e32 v104, v101
	v_mov_b32_e32 v105, v102
	v_mov_b32_e32 v101, v103
	v_pk_add_f32 v[100:101], v[104:105], v[100:101]
	s_nop 0
	v_add_f32_e32 v100, v100, v101
	v_fmamk_f32 v100, v100, 0x3a800000, v138
	v_rsq_f32_e32 v100, v100
	s_nop 0
	v_mul_f32_e32 v244, 0xbfb8aa3b, v100
	v_mul_f32_e32 v246, v100, v100
	v_mov_b32_e32 v248, 1.0
	v_pk_mul_f32 v[228:229], v[94:95], v[244:245] op_sel_hi:[1,0]
	v_pk_mul_f32 v[232:233], v[96:97], v[244:245] op_sel_hi:[1,0]
	v_pk_mul_f32 v[236:237], v[90:91], v[244:245] op_sel_hi:[1,0]
	v_pk_mul_f32 v[240:241], v[92:93], v[244:245] op_sel_hi:[1,0]
	v_exp_f32_e32 v228, v228
	v_exp_f32_e32 v229, v229
	v_exp_f32_e32 v232, v232
	v_exp_f32_e32 v233, v233
	v_exp_f32_e32 v236, v236
	v_exp_f32_e32 v237, v237
	v_exp_f32_e32 v240, v240
	v_exp_f32_e32 v241, v241
	v_pk_mul_f32 v[230:231], v[94:95], v[86:87]
	v_pk_mul_f32 v[234:235], v[96:97], v[88:89]
	v_pk_mul_f32 v[238:239], v[90:91], v[82:83]
	v_pk_mul_f32 v[242:243], v[92:93], v[84:85]
	v_pk_add_f32 v[228:229], v[228:229], v[248:249] op_sel_hi:[1,0]
	v_pk_add_f32 v[232:233], v[232:233], v[248:249] op_sel_hi:[1,0]
	v_pk_add_f32 v[236:237], v[236:237], v[248:249] op_sel_hi:[1,0]
	v_pk_add_f32 v[240:241], v[240:241], v[248:249] op_sel_hi:[1,0]
	v_rcp_f32_e32 v228, v228
	v_rcp_f32_e32 v229, v229
	v_rcp_f32_e32 v232, v232
	v_rcp_f32_e32 v233, v233
	v_rcp_f32_e32 v236, v236
	v_rcp_f32_e32 v237, v237
	v_rcp_f32_e32 v240, v240
	v_rcp_f32_e32 v241, v241
	v_pk_mul_f32 v[230:231], v[230:231], v[246:247] op_sel_hi:[1,0]
	v_pk_mul_f32 v[234:235], v[234:235], v[246:247] op_sel_hi:[1,0]
	v_pk_mul_f32 v[238:239], v[238:239], v[246:247] op_sel_hi:[1,0]
	v_pk_mul_f32 v[242:243], v[242:243], v[246:247] op_sel_hi:[1,0]
	v_pk_mul_f32 v[230:231], v[230:231], v[228:229]
	v_pk_mul_f32 v[234:235], v[234:235], v[232:233]
	v_pk_mul_f32 v[238:239], v[238:239], v[236:237]
	v_pk_mul_f32 v[242:243], v[242:243], v[240:241]
	v_cvt_pk_bf16_f32 v82, v230, v231
	v_cvt_pk_bf16_f32 v83, v234, v235
	v_cvt_pk_bf16_f32 v84, v238, v239
	v_cvt_pk_bf16_f32 v85, v242, v243
	global_store_dwordx4 v[98:99], v[82:85], off
	s_nop 1
	v_or_b32_e32 v84, 48, v148
	v_ashrrev_i32_e32 v85, 31, v84
	v_mad_i64_i32 v[82:83], s[0:1], v84, s4, v[144:145]
	v_lshl_add_u64 v[84:85], v[84:85], 4, s[24:25]
	v_lshl_add_u64 v[82:83], v[82:83], 0, v[146:147]
	s_waitcnt vmcnt(7)
	v_mov_b64_e32 v[84:85], v[202:203]
	v_mov_b64_e32 v[86:87], v[204:205]
	v_mov_b32_e32 v88, v85
	v_mov_b32_e32 v89, v86
	v_mov_b32_e32 v85, v87
	v_pk_add_f32 v[84:85], v[88:89], v[84:85]
	s_nop 0
	v_add_f32_e32 v84, v84, v85
	v_fmamk_f32 v84, v84, 0x3a800000, v138
	v_rsq_f32_e32 v84, v84
	s_nop 0
	v_mul_f32_e32 v244, 0xbfb8aa3b, v84
	v_mul_f32_e32 v246, v84, v84
	v_mov_b32_e32 v248, 1.0
	v_pk_mul_f32 v[228:229], v[78:79], v[244:245] op_sel_hi:[1,0]
	v_pk_mul_f32 v[232:233], v[80:81], v[244:245] op_sel_hi:[1,0]
	v_pk_mul_f32 v[236:237], v[74:75], v[244:245] op_sel_hi:[1,0]
	v_pk_mul_f32 v[240:241], v[76:77], v[244:245] op_sel_hi:[1,0]
	v_exp_f32_e32 v228, v228
	v_exp_f32_e32 v229, v229
	v_exp_f32_e32 v232, v232
	v_exp_f32_e32 v233, v233
	v_exp_f32_e32 v236, v236
	v_exp_f32_e32 v237, v237
	v_exp_f32_e32 v240, v240
	v_exp_f32_e32 v241, v241
	v_pk_mul_f32 v[230:231], v[78:79], v[70:71]
	v_pk_mul_f32 v[234:235], v[80:81], v[72:73]
	v_pk_mul_f32 v[238:239], v[74:75], v[66:67]
	v_pk_mul_f32 v[242:243], v[76:77], v[68:69]
	v_pk_add_f32 v[228:229], v[228:229], v[248:249] op_sel_hi:[1,0]
	v_pk_add_f32 v[232:233], v[232:233], v[248:249] op_sel_hi:[1,0]
	v_pk_add_f32 v[236:237], v[236:237], v[248:249] op_sel_hi:[1,0]
	v_pk_add_f32 v[240:241], v[240:241], v[248:249] op_sel_hi:[1,0]
	v_rcp_f32_e32 v228, v228
	v_rcp_f32_e32 v229, v229
	v_rcp_f32_e32 v232, v232
	v_rcp_f32_e32 v233, v233
	v_rcp_f32_e32 v236, v236
	v_rcp_f32_e32 v237, v237
	v_rcp_f32_e32 v240, v240
	v_rcp_f32_e32 v241, v241
	v_pk_mul_f32 v[230:231], v[230:231], v[246:247] op_sel_hi:[1,0]
	v_pk_mul_f32 v[234:235], v[234:235], v[246:247] op_sel_hi:[1,0]
	v_pk_mul_f32 v[238:239], v[238:239], v[246:247] op_sel_hi:[1,0]
	v_pk_mul_f32 v[242:243], v[242:243], v[246:247] op_sel_hi:[1,0]
	v_pk_mul_f32 v[230:231], v[230:231], v[228:229]
	v_pk_mul_f32 v[234:235], v[234:235], v[232:233]
	v_pk_mul_f32 v[238:239], v[238:239], v[236:237]
	v_pk_mul_f32 v[242:243], v[242:243], v[240:241]
	v_cvt_pk_bf16_f32 v66, v230, v231
	v_cvt_pk_bf16_f32 v67, v234, v235
	v_cvt_pk_bf16_f32 v68, v238, v239
	v_cvt_pk_bf16_f32 v69, v242, v243
	global_store_dwordx4 v[82:83], v[66:69], off
	s_nop 1
	v_add_u32_e32 v68, 0x80, v148
	v_ashrrev_i32_e32 v69, 31, v68
	v_mad_i64_i32 v[66:67], s[0:1], v68, s4, v[144:145]
	v_lshl_add_u64 v[68:69], v[68:69], 4, s[24:25]
	v_lshl_add_u64 v[66:67], v[66:67], 0, v[146:147]
	s_waitcnt vmcnt(7)
; __device__ __forceinline__ unsigned cvt_pk_bf16(float lo, float hi) { unsigned r; asm volatile("v_cvt_pk_bf16_f32 %0, %1, %2" : "=v"(r) : "v"(lo), "v"(hi)); return r; }
; __device__ __forceinline__ float silu_f(float g) { return g * __builtin_amdgcn_rcpf(1.0f + __expf(-g)); }
; __device__ __forceinline__ float row_rstd(const float* rss, int row) { if (!rss) return 1.0f; const f32x4 s = *(const f32x4*)(rss + 4 * (size_t)row); return __builtin_amdgcn_rsqf(((s[0] + s[1]) + (s[2] + s[3])) * (1.0f / 1024.0f) + 1e-6f); }
;     __device__ __forceinline__ void operator()(const f32x4 (&acc)[2][2][4][2], const Unit& u, int wr, int wc, int fr, int fq) const {
;     ...
;             for (int m = 0; m < 4; ++m) { const int row = row0 + ai * HALF + m * 16; bf16_t* rowp = O + (size_t)row * ldc + col0; const float rs = row_rstd(rss, row);
;                 const f32x4 g0 = acc[ai][0][m][0] * rs, g1 = acc[ai][0][m][1] * rs, u0 = acc[ai][1][m][0] * rs, u1 = acc[ai][1][m][1] * rs;
;                 u32x4 w;
;                 w.x = cvt_pk_bf16(silu_f(g0[0]) * u0[0], silu_f(g0[1]) * u0[1]); w.y = cvt_pk_bf16(silu_f(g0[2]) * u0[2], silu_f(g0[3]) * u0[3]);
;                 w.z = cvt_pk_bf16(silu_f(g1[0]) * u1[0], silu_f(g1[1]) * u1[1]); w.w = cvt_pk_bf16(silu_f(g1[2]) * u1[2], silu_f(g1[3]) * u1[3]);
;                 *(u32x4*)rowp = w; }
	v_mov_b64_e32 v[68:69], v[206:207]
	v_mov_b64_e32 v[70:71], v[208:209]
	v_mov_b32_e32 v72, v69
	v_mov_b32_e32 v73, v70
	v_mov_b32_e32 v69, v71
	v_pk_add_f32 v[68:69], v[72:73], v[68:69]
	s_nop 0
	v_add_f32_e32 v68, v68, v69
	v_fmamk_f32 v68, v68, 0x3a800000, v138
	v_rsq_f32_e32 v68, v68
	s_nop 0
	v_mul_f32_e32 v244, 0xbfb8aa3b, v68
	v_mul_f32_e32 v246, v68, v68
	v_mov_b32_e32 v248, 1.0
	v_pk_mul_f32 v[228:229], v[62:63], v[244:245] op_sel_hi:[1,0]
	v_pk_mul_f32 v[232:233], v[64:65], v[244:245] op_sel_hi:[1,0]
	v_pk_mul_f32 v[236:237], v[58:59], v[244:245] op_sel_hi:[1,0]
	v_pk_mul_f32 v[240:241], v[60:61], v[244:245] op_sel_hi:[1,0]
	v_exp_f32_e32 v228, v228
	v_exp_f32_e32 v229, v229
	v_exp_f32_e32 v232, v232
	v_exp_f32_e32 v233, v233
	v_exp_f32_e32 v236, v236
	v_exp_f32_e32 v237, v237
	v_exp_f32_e32 v240, v240
	v_exp_f32_e32 v241, v241
	v_pk_mul_f32 v[230:231], v[62:63], v[54:55]
	v_pk_mul_f32 v[234:235], v[64:65], v[56:57]
	v_pk_mul_f32 v[238:239], v[58:59], v[50:51]
	v_pk_mul_f32 v[242:243], v[60:61], v[52:53]
	v_pk_add_f32 v[228:229], v[228:229], v[248:249] op_sel_hi:[1,0]
	v_pk_add_f32 v[232:233], v[232:233], v[248:249] op_sel_hi:[1,0]
	v_pk_add_f32 v[236:237], v[236:237], v[248:249] op_sel_hi:[1,0]
	v_pk_add_f32 v[240:241], v[240:241], v[248:249] op_sel_hi:[1,0]
	v_rcp_f32_e32 v228, v228
	v_rcp_f32_e32 v229, v229
	v_rcp_f32_e32 v232, v232
	v_rcp_f32_e32 v233, v233
	v_rcp_f32_e32 v236, v236
	v_rcp_f32_e32 v237, v237
	v_rcp_f32_e32 v240, v240
	v_rcp_f32_e32 v241, v241
	v_pk_mul_f32 v[230:231], v[230:231], v[246:247] op_sel_hi:[1,0]
	v_pk_mul_f32 v[234:235], v[234:235], v[246:247] op_sel_hi:[1,0]
	v_pk_mul_f32 v[238:239], v[238:239], v[246:247] op_sel_hi:[1,0]
	v_pk_mul_f32 v[242:243], v[242:243], v[246:247] op_sel_hi:[1,0]
	v_pk_mul_f32 v[230:231], v[230:231], v[228:229]
	v_pk_mul_f32 v[234:235], v[234:235], v[232:233]
	v_pk_mul_f32 v[238:239], v[238:239], v[236:237]
	v_pk_mul_f32 v[242:243], v[242:243], v[240:241]
	v_cvt_pk_bf16_f32 v50, v230, v231
	v_cvt_pk_bf16_f32 v51, v234, v235
	v_cvt_pk_bf16_f32 v52, v238, v239
	v_cvt_pk_bf16_f32 v53, v242, v243
	global_store_dwordx4 v[66:67], v[50:53], off
	s_nop 1
	v_add_u32_e32 v52, 0x90, v148
	v_ashrrev_i32_e32 v53, 31, v52
	v_mad_i64_i32 v[50:51], s[0:1], v52, s4, v[144:145]
	v_lshl_add_u64 v[52:53], v[52:53], 4, s[24:25]
	v_lshl_add_u64 v[50:51], v[50:51], 0, v[146:147]
	s_waitcnt vmcnt(7)
	v_mov_b64_e32 v[52:53], v[210:211]
	v_mov_b64_e32 v[54:55], v[212:213]
	v_mov_b32_e32 v56, v53
	v_mov_b32_e32 v57, v54
	v_mov_b32_e32 v53, v55
	v_pk_add_f32 v[52:53], v[56:57], v[52:53]
	s_nop 0
	v_add_f32_e32 v52, v52, v53
	v_fmamk_f32 v52, v52, 0x3a800000, v138
	v_rsq_f32_e32 v52, v52
	s_nop 0
	v_mul_f32_e32 v244, 0xbfb8aa3b, v52
	v_mul_f32_e32 v246, v52, v52
	v_mov_b32_e32 v248, 1.0
	v_pk_mul_f32 v[228:229], v[46:47], v[244:245] op_sel_hi:[1,0]
	v_pk_mul_f32 v[232:233], v[48:49], v[244:245] op_sel_hi:[1,0]
	v_pk_mul_f32 v[236:237], v[42:43], v[244:245] op_sel_hi:[1,0]
	v_pk_mul_f32 v[240:241], v[44:45], v[244:245] op_sel_hi:[1,0]
	v_exp_f32_e32 v228, v228
	v_exp_f32_e32 v229, v229
	v_exp_f32_e32 v232, v232
	v_exp_f32_e32 v233, v233
	v_exp_f32_e32 v236, v236
	v_exp_f32_e32 v237, v237
	v_exp_f32_e32 v240, v240
	v_exp_f32_e32 v241, v241
	v_pk_mul_f32 v[230:231], v[46:47], v[38:39]
	v_pk_mul_f32 v[234:235], v[48:49], v[40:41]
	v_pk_mul_f32 v[238:239], v[42:43], v[34:35]
	v_pk_mul_f32 v[242:243], v[44:45], v[36:37]
	v_pk_add_f32 v[228:229], v[228:229], v[248:249] op_sel_hi:[1,0]
	v_pk_add_f32 v[232:233], v[232:233], v[248:249] op_sel_hi:[1,0]
	v_pk_add_f32 v[236:237], v[236:237], v[248:249] op_sel_hi:[1,0]
	v_pk_add_f32 v[240:241], v[240:241], v[248:249] op_sel_hi:[1,0]
	v_rcp_f32_e32 v228, v228
	v_rcp_f32_e32 v229, v229
	v_rcp_f32_e32 v232, v232
	v_rcp_f32_e32 v233, v233
	v_rcp_f32_e32 v236, v236
	v_rcp_f32_e32 v237, v237
	v_rcp_f32_e32 v240, v240
	v_rcp_f32_e32 v241, v241
	v_pk_mul_f32 v[230:231], v[230:231], v[246:247] op_sel_hi:[1,0]
	v_pk_mul_f32 v[234:235], v[234:235], v[246:247] op_sel_hi:[1,0]
	v_pk_mul_f32 v[238:239], v[238:239], v[246:247] op_sel_hi:[1,0]
	v_pk_mul_f32 v[242:243], v[242:243], v[246:247] op_sel_hi:[1,0]
	v_pk_mul_f32 v[230:231], v[230:231], v[228:229]
	v_pk_mul_f32 v[234:235], v[234:235], v[232:233]
	v_pk_mul_f32 v[238:239], v[238:239], v[236:237]
	v_pk_mul_f32 v[242:243], v[242:243], v[240:241]
	v_cvt_pk_bf16_f32 v34, v230, v231
	v_cvt_pk_bf16_f32 v35, v234, v235
	v_cvt_pk_bf16_f32 v36, v238, v239
	v_cvt_pk_bf16_f32 v37, v242, v243
	global_store_dwordx4 v[50:51], v[34:37], off
	s_nop 1
	v_add_u32_e32 v36, 0xa0, v148
	v_ashrrev_i32_e32 v37, 31, v36
	v_mad_i64_i32 v[34:35], s[0:1], v36, s4, v[144:145]
	v_lshl_add_u64 v[36:37], v[36:37], 4, s[24:25]
	v_lshl_add_u64 v[34:35], v[34:35], 0, v[146:147]
	s_waitcnt vmcnt(7)
; __device__ __forceinline__ unsigned cvt_pk_bf16(float lo, float hi) { unsigned r; asm volatile("v_cvt_pk_bf16_f32 %0, %1, %2" : "=v"(r) : "v"(lo), "v"(hi)); return r; }
; __device__ __forceinline__ float silu_f(float g) { return g * __builtin_amdgcn_rcpf(1.0f + __expf(-g)); }
; __device__ __forceinline__ float row_rstd(const float* rss, int row) { if (!rss) return 1.0f; const f32x4 s = *(const f32x4*)(rss + 4 * (size_t)row); return __builtin_amdgcn_rsqf(((s[0] + s[1]) + (s[2] + s[3])) * (1.0f / 1024.0f) + 1e-6f); }
;     __device__ __forceinline__ void operator()(const f32x4 (&acc)[2][2][4][2], const Unit& u, int wr, int wc, int fr, int fq) const {
;     ...
;             for (int m = 0; m < 4; ++m) { const int row = row0 + ai * HALF + m * 16; bf16_t* rowp = O + (size_t)row * ldc + col0; const float rs = row_rstd(rss, row);
;                 const f32x4 g0 = acc[ai][0][m][0] * rs, g1 = acc[ai][0][m][1] * rs, u0 = acc[ai][1][m][0] * rs, u1 = acc[ai][1][m][1] * rs;
;                 u32x4 w;
;                 w.x = cvt_pk_bf16(silu_f(g0[0]) * u0[0], silu_f(g0[1]) * u0[1]); w.y = cvt_pk_bf16(silu_f(g0[2]) * u0[2], silu_f(g0[3]) * u0[3]);
;                 w.z = cvt_pk_bf16(silu_f(g1[0]) * u1[0], silu_f(g1[1]) * u1[1]); w.w = cvt_pk_bf16(silu_f(g1[2]) * u1[2], silu_f(g1[3]) * u1[3]);
;                 *(u32x4*)rowp = w; }
	v_mov_b64_e32 v[36:37], v[214:215]
	v_mov_b64_e32 v[38:39], v[216:217]
	v_mov_b32_e32 v40, v37
	v_mov_b32_e32 v41, v38
	v_mov_b32_e32 v37, v39
	v_pk_add_f32 v[36:37], v[40:41], v[36:37]
	s_nop 0
	v_add_f32_e32 v36, v36, v37
	v_fmamk_f32 v36, v36, 0x3a800000, v138
	v_rsq_f32_e32 v36, v36
	s_nop 0
	v_mul_f32_e32 v244, 0xbfb8aa3b, v36
	v_mul_f32_e32 v246, v36, v36
	v_mov_b32_e32 v248, 1.0
	v_pk_mul_f32 v[228:229], v[30:31], v[244:245] op_sel_hi:[1,0]
	v_pk_mul_f32 v[232:233], v[32:33], v[244:245] op_sel_hi:[1,0]
	v_pk_mul_f32 v[236:237], v[26:27], v[244:245] op_sel_hi:[1,0]
	v_pk_mul_f32 v[240:241], v[28:29], v[244:245] op_sel_hi:[1,0]
	v_exp_f32_e32 v228, v228
	v_exp_f32_e32 v229, v229
	v_exp_f32_e32 v232, v232
	v_exp_f32_e32 v233, v233
	v_exp_f32_e32 v236, v236
	v_exp_f32_e32 v237, v237
	v_exp_f32_e32 v240, v240
	v_exp_f32_e32 v241, v241
	v_pk_mul_f32 v[230:231], v[30:31], v[22:23]
	v_pk_mul_f32 v[234:235], v[32:33], v[24:25]
	v_pk_mul_f32 v[238:239], v[26:27], v[18:19]
	v_pk_mul_f32 v[242:243], v[28:29], v[20:21]
	v_pk_add_f32 v[228:229], v[228:229], v[248:249] op_sel_hi:[1,0]
	v_pk_add_f32 v[232:233], v[232:233], v[248:249] op_sel_hi:[1,0]
	v_pk_add_f32 v[236:237], v[236:237], v[248:249] op_sel_hi:[1,0]
	v_pk_add_f32 v[240:241], v[240:241], v[248:249] op_sel_hi:[1,0]
	v_rcp_f32_e32 v228, v228
	v_rcp_f32_e32 v229, v229
	v_rcp_f32_e32 v232, v232
	v_rcp_f32_e32 v233, v233
	v_rcp_f32_e32 v236, v236
	v_rcp_f32_e32 v237, v237
	v_rcp_f32_e32 v240, v240
	v_rcp_f32_e32 v241, v241
	v_pk_mul_f32 v[230:231], v[230:231], v[246:247] op_sel_hi:[1,0]
	v_pk_mul_f32 v[234:235], v[234:235], v[246:247] op_sel_hi:[1,0]
	v_pk_mul_f32 v[238:239], v[238:239], v[246:247] op_sel_hi:[1,0]
	v_pk_mul_f32 v[242:243], v[242:243], v[246:247] op_sel_hi:[1,0]
	v_pk_mul_f32 v[230:231], v[230:231], v[228:229]
	v_pk_mul_f32 v[234:235], v[234:235], v[232:233]
	v_pk_mul_f32 v[238:239], v[238:239], v[236:237]
	v_pk_mul_f32 v[242:243], v[242:243], v[240:241]
	v_cvt_pk_bf16_f32 v18, v230, v231
	v_cvt_pk_bf16_f32 v19, v234, v235
	v_cvt_pk_bf16_f32 v20, v238, v239
	v_cvt_pk_bf16_f32 v21, v242, v243
	global_store_dwordx4 v[34:35], v[18:21], off
	s_nop 1
	v_add_u32_e32 v18, 0xb0, v148
	v_ashrrev_i32_e32 v19, 31, v18
	v_lshl_add_u64 v[20:21], v[18:19], 4, s[24:25]
	s_waitcnt vmcnt(7)
	v_mov_b64_e32 v[20:21], v[218:219]
	v_mov_b64_e32 v[22:23], v[220:221]
	v_mov_b32_e32 v24, v21
	v_mov_b32_e32 v25, v22
	v_mov_b32_e32 v21, v23
	v_pk_add_f32 v[20:21], v[24:25], v[20:21]
	s_nop 0
	v_add_f32_e32 v19, v20, v21
	v_fmamk_f32 v19, v19, 0x3a800000, v138
	v_rsq_f32_e32 v20, v19
	s_nop 0
	v_mad_i64_i32 v[18:19], s[0:1], v18, s4, v[144:145]
	v_lshl_add_u64 v[18:19], v[18:19], 0, v[146:147]
	v_mul_f32_e32 v244, 0xbfb8aa3b, v20
	v_mul_f32_e32 v246, v20, v20
	v_mov_b32_e32 v248, 1.0
	v_pk_mul_f32 v[228:229], v[14:15], v[244:245] op_sel_hi:[1,0]
	v_pk_mul_f32 v[232:233], v[16:17], v[244:245] op_sel_hi:[1,0]
	v_pk_mul_f32 v[236:237], v[10:11], v[244:245] op_sel_hi:[1,0]
	v_pk_mul_f32 v[240:241], v[12:13], v[244:245] op_sel_hi:[1,0]
	v_exp_f32_e32 v228, v228
	v_exp_f32_e32 v229, v229
	v_exp_f32_e32 v232, v232
	v_exp_f32_e32 v233, v233
	v_exp_f32_e32 v236, v236
	v_exp_f32_e32 v237, v237
	v_exp_f32_e32 v240, v240
	v_exp_f32_e32 v241, v241
	v_pk_mul_f32 v[230:231], v[14:15], v[6:7]
	v_pk_mul_f32 v[234:235], v[16:17], v[8:9]
	v_pk_mul_f32 v[238:239], v[10:11], v[2:3]
	v_pk_mul_f32 v[242:243], v[12:13], v[4:5]
	v_pk_add_f32 v[228:229], v[228:229], v[248:249] op_sel_hi:[1,0]
	v_pk_add_f32 v[232:233], v[232:233], v[248:249] op_sel_hi:[1,0]
	v_pk_add_f32 v[236:237], v[236:237], v[248:249] op_sel_hi:[1,0]
	v_pk_add_f32 v[240:241], v[240:241], v[248:249] op_sel_hi:[1,0]
	v_rcp_f32_e32 v228, v228
	v_rcp_f32_e32 v229, v229
	v_rcp_f32_e32 v232, v232
	v_rcp_f32_e32 v233, v233
	v_rcp_f32_e32 v236, v236
	v_rcp_f32_e32 v237, v237
	v_rcp_f32_e32 v240, v240
	v_rcp_f32_e32 v241, v241
	v_pk_mul_f32 v[230:231], v[230:231], v[246:247] op_sel_hi:[1,0]
	v_pk_mul_f32 v[234:235], v[234:235], v[246:247] op_sel_hi:[1,0]
	v_pk_mul_f32 v[238:239], v[238:239], v[246:247] op_sel_hi:[1,0]
	v_pk_mul_f32 v[242:243], v[242:243], v[246:247] op_sel_hi:[1,0]
	v_pk_mul_f32 v[230:231], v[230:231], v[228:229]
	v_pk_mul_f32 v[234:235], v[234:235], v[232:233]
	v_pk_mul_f32 v[238:239], v[238:239], v[236:237]
	v_pk_mul_f32 v[242:243], v[242:243], v[240:241]
	v_cvt_pk_bf16_f32 v2, v230, v231
	v_cvt_pk_bf16_f32 v3, v234, v235
	v_cvt_pk_bf16_f32 v4, v238, v239
	v_cvt_pk_bf16_f32 v5, v242, v243
	global_store_dwordx4 v[18:19], v[2:5], off
	s_cbranch_vccnz .LBB0_1121
	s_andn2_b64 vcc, exec, s[20:21]
	s_cbranch_vccnz .LBB0_1120
	s_barrier
	s_branch .LBB0_1120
